# GEMM K-loops: inner s_setprio 0/1 flip between the two 16-MFMA groups of a phase removed
# baseline (speedup 1.0000x reference)
; #define PG8_STAGE(bufoff, gbase, voff) do { _Pragma("unroll") for (int _i = 0; _i < 2; ++_i) \
;         __builtin_amdgcn_global_load_lds((const unsigned*)((const char*)(gbase) + (voff)[_i]), (PG8_LAS unsigned*)(lds + (bufoff) + ldsw + _i * 8192), 16, 0, 0); } while (0)
; #define PG8_LDA(dst, b, h) do { _Pragma("unroll") for (int m = 0; m < 4; ++m) _Pragma("unroll") for (int k = 0; k < 2; ++k) dst[m][k] = *(const PG8_LAS bf16x8*)(lds + PG8_SA(b, h) + aoff + m * 2048 + k * 1024); } while (0)
; #define PG8_LDB(dst, b, h) do { _Pragma("unroll") for (int n = 0; n < 2; ++n) _Pragma("unroll") for (int k = 0; k < 2; ++k) dst[n][k] = *(const PG8_LAS bf16x8*)(lds + PG8_SB(b, h) + boff + n * 2048 + k * 1024); } while (0)
; #define PG8_MMA(ai, bj, At, Bt) do { __builtin_amdgcn_s_setprio(1); _Pragma("unroll") for (int m = 0; m < 4; ++m) _Pragma("unroll") for (int n = 0; n < 2; ++n) _Pragma("unroll") for (int k = 0; k < 2; ++k) \
;         acc[ai][bj][m][n] = __builtin_amdgcn_mfma_f32_16x16x32_bf16(Bt[n][k], At[m][k], acc[ai][bj][m][n], 0, 0, 0); __builtin_amdgcn_s_setprio(0); } while (0)
; #define PG8_WAIT_V(n) asm volatile("s_waitcnt vmcnt(" #n ")" ::: "memory")
; #define PG8_WAIT_L(n) asm volatile("s_waitcnt lgkmcnt(" #n ")" ::: "memory")
; #define PG8_BAR __builtin_amdgcn_s_barrier()
; #define PG8_SCHED __builtin_amdgcn_sched_barrier(0)
; template <class Epi, class Sched>
; __device__ __forceinline__ void gemm_phase(PG8_LAS unsigned char* lds, const Gemm g, const Sched& S, const Epi& E) {
;     ...
;             PG8_LDB(B0, 0, 0); PG8_LDB(B1, 0, 1); PG8_SCHED; PG8_LDA(At, 0, 0); PG8_STAGE(PG8_SA(1, 1), a1 + hstepA, voffA);
;             PG8_WAIT_V(8); PG8_WAIT_L(0); PG8_BAR; PG8_MMA(0, 0, At, B0); PG8_MMA(0, 1, At, B1); PG8_BAR; PG8_SCHED;
;             PG8_LDA(At, 0, 1); PG8_STAGE(PG8_SB(0, 0), b2, voffB); PG8_STAGE(PG8_SB(0, 1), b2 + hstepB, voffB); PG8_STAGE(PG8_SA(0, 0), a2, voffA);
;             PG8_WAIT_V(8); PG8_WAIT_L(0); PG8_BAR; PG8_MMA(1, 0, At, B0); PG8_MMA(1, 1, At, B1); PG8_BAR; PG8_SCHED;
.LBB0_24:
	s_add_u32 s9, s28, 0xfff80080
	s_addc_u32 s10, s29, -1
	s_add_i32 s11, 0, 0x10000
	s_cmp_eq_u32 s8, 28
	s_cselect_b32 s43, s5, s10
	s_cselect_b32 s42, s13, s9
	v_add_u32_e32 v140, s11, v143
	s_cselect_b32 s39, s59, s7
	s_cselect_b32 s38, s61, s6
	s_add_i32 s9, 0, 0x14000
	ds_read_b128 v[146:149], v140
	ds_read_b128 v[150:153], v140 offset:1024
	ds_read_b128 v[154:157], v140 offset:2048
	ds_read_b128 v[158:161], v140 offset:3072
	v_add_u32_e32 v140, s9, v143
	ds_read_b128 v[170:173], v140
	ds_read_b128 v[174:177], v140 offset:1024
	ds_read_b128 v[178:181], v140 offset:2048
	ds_read_b128 v[182:185], v140 offset:3072
	v_lshl_add_u64 v[140:141], s[28:29], 0, v[136:137]
	s_add_i32 m0, s82, 0xc000
	ds_read_b128 v[186:189], v145
	ds_read_b128 v[190:193], v145 offset:1024
	ds_read_b128 v[194:197], v145 offset:2048
	ds_read_b128 v[198:201], v145 offset:3072
	ds_read_b128 v[202:205], v145 offset:4096
	ds_read_b128 v[216:219], v145 offset:5120
	ds_read_b128 v[220:223], v145 offset:6144
	ds_read_b128 v[224:227], v145 offset:7168
	global_load_lds_dwordx4 v[140:141], off
	v_lshl_add_u64 v[140:141], s[28:29], 0, v[138:139]
	s_add_i32 m0, s82, 0xe000
	s_nop 0
	global_load_lds_dwordx4 v[140:141], off
	s_waitcnt vmcnt(8)
	s_waitcnt lgkmcnt(0)
	s_barrier
	s_setprio 1
	s_waitcnt lgkmcnt(0)
	v_mfma_f32_16x16x32_bf16 v[118:121], v[146:149], v[186:189], v[118:121]
	v_mfma_f32_16x16x32_bf16 v[114:117], v[154:157], v[186:189], v[114:117]
	v_mfma_f32_16x16x32_bf16 v[110:113], v[146:149], v[194:197], v[110:113]
	v_mfma_f32_16x16x32_bf16 v[102:105], v[154:157], v[194:197], v[102:105]
	v_mfma_f32_16x16x32_bf16 v[86:89], v[146:149], v[202:205], v[86:89]
	v_mfma_f32_16x16x32_bf16 v[82:85], v[154:157], v[202:205], v[82:85]
	v_mfma_f32_16x16x32_bf16 v[78:81], v[146:149], v[220:223], v[78:81]
	v_mfma_f32_16x16x32_bf16 v[70:73], v[154:157], v[220:223], v[70:73]
	v_mfma_f32_16x16x32_bf16 v[118:121], v[150:153], v[190:193], v[118:121]
	v_mfma_f32_16x16x32_bf16 v[114:117], v[158:161], v[190:193], v[114:117]
	v_mfma_f32_16x16x32_bf16 v[110:113], v[150:153], v[198:201], v[110:113]
	v_mfma_f32_16x16x32_bf16 v[102:105], v[158:161], v[198:201], v[102:105]
	v_mfma_f32_16x16x32_bf16 v[86:89], v[150:153], v[216:219], v[86:89]
	v_mfma_f32_16x16x32_bf16 v[82:85], v[158:161], v[216:219], v[82:85]
	v_mfma_f32_16x16x32_bf16 v[78:81], v[150:153], v[224:227], v[78:81]
	v_mfma_f32_16x16x32_bf16 v[70:73], v[158:161], v[224:227], v[70:73]
	v_mfma_f32_16x16x32_bf16 v[126:129], v[170:173], v[186:189], v[126:129]
	v_mfma_f32_16x16x32_bf16 v[122:125], v[178:181], v[186:189], v[122:125]
	v_mfma_f32_16x16x32_bf16 v[106:109], v[170:173], v[194:197], v[106:109]
	v_mfma_f32_16x16x32_bf16 v[98:101], v[178:181], v[194:197], v[98:101]
	v_mfma_f32_16x16x32_bf16 v[94:97], v[170:173], v[202:205], v[94:97]
	v_mfma_f32_16x16x32_bf16 v[90:93], v[178:181], v[202:205], v[90:93]
	v_mfma_f32_16x16x32_bf16 v[74:77], v[170:173], v[220:223], v[74:77]
	v_mfma_f32_16x16x32_bf16 v[66:69], v[178:181], v[220:223], v[66:69]
	v_mfma_f32_16x16x32_bf16 v[126:129], v[174:177], v[190:193], v[126:129]
	v_mfma_f32_16x16x32_bf16 v[122:125], v[182:185], v[190:193], v[122:125]
	v_mfma_f32_16x16x32_bf16 v[106:109], v[174:177], v[198:201], v[106:109]
	v_mfma_f32_16x16x32_bf16 v[98:101], v[182:185], v[198:201], v[98:101]
	v_mfma_f32_16x16x32_bf16 v[94:97], v[174:177], v[216:219], v[94:97]
	v_mfma_f32_16x16x32_bf16 v[90:93], v[182:185], v[216:219], v[90:93]
	v_mfma_f32_16x16x32_bf16 v[74:77], v[174:177], v[224:227], v[74:77]
	v_mfma_f32_16x16x32_bf16 v[66:69], v[182:185], v[224:227], v[66:69]
	s_setprio 0
	s_barrier
	s_add_i32 s10, s11, s80
	v_lshl_add_u64 v[140:141], s[38:39], 0, v[0:1]
	s_mov_b32 m0, s10
	ds_read_b128 v[186:189], v145 offset:16384
	ds_read_b128 v[190:193], v145 offset:17408
	ds_read_b128 v[194:197], v145 offset:18432
	ds_read_b128 v[198:201], v145 offset:19456
	ds_read_b128 v[202:205], v145 offset:20480
	ds_read_b128 v[216:219], v145 offset:21504
	ds_read_b128 v[220:223], v145 offset:22528
	ds_read_b128 v[224:227], v145 offset:23552
	global_load_lds_dwordx4 v[140:141], off
	s_add_i32 m0, s10, 0x2000
	s_add_u32 s10, s38, 0x80000
	v_lshl_add_u64 v[168:169], s[38:39], 0, v[130:131]
	s_addc_u32 s11, s39, 0
	s_add_i32 s9, s9, s80
	global_load_lds_dwordx4 v[168:169], off
	v_lshl_add_u64 v[228:229], s[10:11], 0, v[0:1]
	s_mov_b32 m0, s9
	v_lshl_add_u64 v[230:231], s[42:43], 0, v[132:133]
	global_load_lds_dwordx4 v[228:229], off
	v_lshl_add_u64 v[228:229], s[10:11], 0, v[130:131]
	s_add_i32 m0, s9, 0x2000
	s_nop 0
	global_load_lds_dwordx4 v[228:229], off
	v_lshl_add_u64 v[228:229], s[42:43], 0, v[134:135]
	s_mov_b32 m0, s82
	s_nop 0
	global_load_lds_dwordx4 v[228:229], off
	s_mov_b32 m0, s83
	s_nop 0
	global_load_lds_dwordx4 v[230:231], off
	s_waitcnt vmcnt(8)
	s_waitcnt lgkmcnt(0)
	s_barrier
; #define PG8_STAGE(bufoff, gbase, voff) do { _Pragma("unroll") for (int _i = 0; _i < 2; ++_i) \
;         __builtin_amdgcn_global_load_lds((const unsigned*)((const char*)(gbase) + (voff)[_i]), (PG8_LAS unsigned*)(lds + (bufoff) + ldsw + _i * 8192), 16, 0, 0); } while (0)
; #define PG8_LDA(dst, b, h) do { _Pragma("unroll") for (int m = 0; m < 4; ++m) _Pragma("unroll") for (int k = 0; k < 2; ++k) dst[m][k] = *(const PG8_LAS bf16x8*)(lds + PG8_SA(b, h) + aoff + m * 2048 + k * 1024); } while (0)
; #define PG8_LDB(dst, b, h) do { _Pragma("unroll") for (int n = 0; n < 2; ++n) _Pragma("unroll") for (int k = 0; k < 2; ++k) dst[n][k] = *(const PG8_LAS bf16x8*)(lds + PG8_SB(b, h) + boff + n * 2048 + k * 1024); } while (0)
; #define PG8_MMA(ai, bj, At, Bt) do { __builtin_amdgcn_s_setprio(1); _Pragma("unroll") for (int m = 0; m < 4; ++m) _Pragma("unroll") for (int n = 0; n < 2; ++n) _Pragma("unroll") for (int k = 0; k < 2; ++k) \
;         acc[ai][bj][m][n] = __builtin_amdgcn_mfma_f32_16x16x32_bf16(Bt[n][k], At[m][k], acc[ai][bj][m][n], 0, 0, 0); __builtin_amdgcn_s_setprio(0); } while (0)
; #define PG8_WAIT_V(n) asm volatile("s_waitcnt vmcnt(" #n ")" ::: "memory")
; #define PG8_WAIT_L(n) asm volatile("s_waitcnt lgkmcnt(" #n ")" ::: "memory")
; #define PG8_BAR __builtin_amdgcn_s_barrier()
; #define PG8_SCHED __builtin_amdgcn_sched_barrier(0)
; template <class Epi, class Sched>
; __device__ __forceinline__ void gemm_phase(PG8_LAS unsigned char* lds, const Gemm g, const Sched& S, const Epi& E) {
;     ...
;             PG8_WAIT_V(8); PG8_WAIT_L(0); PG8_BAR; PG8_MMA(1, 0, At, B0); PG8_MMA(1, 1, At, B1); PG8_BAR; PG8_SCHED;
;             PG8_LDB(B0, 1, 0); PG8_LDB(B1, 1, 1); PG8_SCHED; PG8_LDA(At, 1, 0); PG8_STAGE(PG8_SA(0, 1), a2 + hstepA, voffA);
;             PG8_WAIT_V(8); PG8_WAIT_L(0); PG8_BAR; PG8_MMA(0, 0, At, B0); PG8_MMA(0, 1, At, B1); PG8_BAR; PG8_SCHED;
	s_setprio 1
	s_waitcnt lgkmcnt(0)
	v_mfma_f32_16x16x32_bf16 v[54:57], v[146:149], v[186:189], v[54:57]
	v_mfma_f32_16x16x32_bf16 v[50:53], v[154:157], v[186:189], v[50:53]
	v_mfma_f32_16x16x32_bf16 v[46:49], v[146:149], v[194:197], v[46:49]
	v_mfma_f32_16x16x32_bf16 v[38:41], v[154:157], v[194:197], v[38:41]
	v_mfma_f32_16x16x32_bf16 v[22:25], v[146:149], v[202:205], v[22:25]
	v_mfma_f32_16x16x32_bf16 v[18:21], v[154:157], v[202:205], v[18:21]
	v_mfma_f32_16x16x32_bf16 v[14:17], v[146:149], v[220:223], v[14:17]
	v_mfma_f32_16x16x32_bf16 v[6:9], v[154:157], v[220:223], v[6:9]
	v_mfma_f32_16x16x32_bf16 v[54:57], v[150:153], v[190:193], v[54:57]
	v_mfma_f32_16x16x32_bf16 v[50:53], v[158:161], v[190:193], v[50:53]
	v_mfma_f32_16x16x32_bf16 v[46:49], v[150:153], v[198:201], v[46:49]
	v_mfma_f32_16x16x32_bf16 v[38:41], v[158:161], v[198:201], v[38:41]
	v_mfma_f32_16x16x32_bf16 v[22:25], v[150:153], v[216:219], v[22:25]
	v_mfma_f32_16x16x32_bf16 v[18:21], v[158:161], v[216:219], v[18:21]
	v_mfma_f32_16x16x32_bf16 v[14:17], v[150:153], v[224:227], v[14:17]
	v_mfma_f32_16x16x32_bf16 v[6:9], v[158:161], v[224:227], v[6:9]
	v_mfma_f32_16x16x32_bf16 v[62:65], v[170:173], v[186:189], v[62:65]
	v_mfma_f32_16x16x32_bf16 v[58:61], v[178:181], v[186:189], v[58:61]
	v_mfma_f32_16x16x32_bf16 v[42:45], v[170:173], v[194:197], v[42:45]
	v_mfma_f32_16x16x32_bf16 v[34:37], v[178:181], v[194:197], v[34:37]
	v_mfma_f32_16x16x32_bf16 v[30:33], v[170:173], v[202:205], v[30:33]
	v_mfma_f32_16x16x32_bf16 v[26:29], v[178:181], v[202:205], v[26:29]
	v_mfma_f32_16x16x32_bf16 v[10:13], v[170:173], v[220:223], v[10:13]
	v_mfma_f32_16x16x32_bf16 v[2:5], v[178:181], v[220:223], v[2:5]
	v_mfma_f32_16x16x32_bf16 v[62:65], v[174:177], v[190:193], v[62:65]
	v_mfma_f32_16x16x32_bf16 v[58:61], v[182:185], v[190:193], v[58:61]
	v_mfma_f32_16x16x32_bf16 v[42:45], v[174:177], v[198:201], v[42:45]
	v_mfma_f32_16x16x32_bf16 v[34:37], v[182:185], v[198:201], v[34:37]
	v_mfma_f32_16x16x32_bf16 v[30:33], v[174:177], v[216:219], v[30:33]
	v_mfma_f32_16x16x32_bf16 v[26:29], v[182:185], v[216:219], v[26:29]
	v_mfma_f32_16x16x32_bf16 v[10:13], v[174:177], v[224:227], v[10:13]
	v_mfma_f32_16x16x32_bf16 v[2:5], v[182:185], v[224:227], v[2:5]
	s_setprio 0
	s_barrier
	s_add_i32 s9, 0, 0x18000
	s_add_i32 s57, 0, 0x1c000
	v_add_u32_e32 v158, s9, v143
	v_add_u32_e32 v162, s57, v143
	ds_read_b128 v[146:149], v158
	ds_read_b128 v[150:153], v158 offset:1024
	ds_read_b128 v[154:157], v158 offset:2048
	ds_read_b128 v[158:161], v158 offset:3072
	ds_read_b128 v[170:173], v162
	ds_read_b128 v[174:177], v162 offset:1024
	ds_read_b128 v[178:181], v162 offset:2048
	ds_read_b128 v[182:185], v162 offset:3072
	s_add_u32 s10, s42, 0x80000
	s_addc_u32 s11, s43, 0
	s_mov_b32 m0, s84
	v_lshl_add_u64 v[232:233], s[10:11], 0, v[134:135]
	ds_read_b128 v[186:189], v145 offset:32768
	ds_read_b128 v[190:193], v145 offset:33792
	ds_read_b128 v[194:197], v145 offset:34816
	ds_read_b128 v[198:201], v145 offset:35840
	ds_read_b128 v[202:205], v145 offset:36864
	ds_read_b128 v[216:219], v145 offset:37888
	ds_read_b128 v[220:223], v145 offset:38912
	ds_read_b128 v[224:227], v145 offset:39936
	global_load_lds_dwordx4 v[232:233], off
	v_lshl_add_u64 v[232:233], s[10:11], 0, v[132:133]
	s_mov_b32 m0, s85
	s_nop 0
	global_load_lds_dwordx4 v[232:233], off
	s_waitcnt vmcnt(8)
	s_waitcnt lgkmcnt(0)
	s_barrier
	s_setprio 1
	s_waitcnt lgkmcnt(0)
	v_mfma_f32_16x16x32_bf16 v[118:121], v[146:149], v[186:189], v[118:121]
	v_mfma_f32_16x16x32_bf16 v[114:117], v[154:157], v[186:189], v[114:117]
	v_mfma_f32_16x16x32_bf16 v[110:113], v[146:149], v[194:197], v[110:113]
	v_mfma_f32_16x16x32_bf16 v[102:105], v[154:157], v[194:197], v[102:105]
	v_mfma_f32_16x16x32_bf16 v[86:89], v[146:149], v[202:205], v[86:89]
	v_mfma_f32_16x16x32_bf16 v[82:85], v[154:157], v[202:205], v[82:85]
	v_mfma_f32_16x16x32_bf16 v[78:81], v[146:149], v[220:223], v[78:81]
	v_mfma_f32_16x16x32_bf16 v[70:73], v[154:157], v[220:223], v[70:73]
	v_mfma_f32_16x16x32_bf16 v[118:121], v[150:153], v[190:193], v[118:121]
	v_mfma_f32_16x16x32_bf16 v[114:117], v[158:161], v[190:193], v[114:117]
	v_mfma_f32_16x16x32_bf16 v[110:113], v[150:153], v[198:201], v[110:113]
	v_mfma_f32_16x16x32_bf16 v[102:105], v[158:161], v[198:201], v[102:105]
	v_mfma_f32_16x16x32_bf16 v[86:89], v[150:153], v[216:219], v[86:89]
	v_mfma_f32_16x16x32_bf16 v[82:85], v[158:161], v[216:219], v[82:85]
	v_mfma_f32_16x16x32_bf16 v[78:81], v[150:153], v[224:227], v[78:81]
	v_mfma_f32_16x16x32_bf16 v[70:73], v[158:161], v[224:227], v[70:73]
	v_mfma_f32_16x16x32_bf16 v[126:129], v[170:173], v[186:189], v[126:129]
	v_mfma_f32_16x16x32_bf16 v[122:125], v[178:181], v[186:189], v[122:125]
	v_mfma_f32_16x16x32_bf16 v[106:109], v[170:173], v[194:197], v[106:109]
	v_mfma_f32_16x16x32_bf16 v[98:101], v[178:181], v[194:197], v[98:101]
	v_mfma_f32_16x16x32_bf16 v[94:97], v[170:173], v[202:205], v[94:97]
	v_mfma_f32_16x16x32_bf16 v[90:93], v[178:181], v[202:205], v[90:93]
	v_mfma_f32_16x16x32_bf16 v[74:77], v[170:173], v[220:223], v[74:77]
	v_mfma_f32_16x16x32_bf16 v[66:69], v[178:181], v[220:223], v[66:69]
	v_mfma_f32_16x16x32_bf16 v[126:129], v[174:177], v[190:193], v[126:129]
	v_mfma_f32_16x16x32_bf16 v[122:125], v[182:185], v[190:193], v[122:125]
	v_mfma_f32_16x16x32_bf16 v[106:109], v[174:177], v[198:201], v[106:109]
	v_mfma_f32_16x16x32_bf16 v[98:101], v[182:185], v[198:201], v[98:101]
	v_mfma_f32_16x16x32_bf16 v[94:97], v[174:177], v[216:219], v[94:97]
	v_mfma_f32_16x16x32_bf16 v[90:93], v[182:185], v[216:219], v[90:93]
	v_mfma_f32_16x16x32_bf16 v[74:77], v[174:177], v[224:227], v[74:77]
	v_mfma_f32_16x16x32_bf16 v[66:69], v[182:185], v[224:227], v[66:69]
	s_setprio 0
	s_barrier
; #define PG8_STAGE(bufoff, gbase, voff) do { _Pragma("unroll") for (int _i = 0; _i < 2; ++_i) \
;         __builtin_amdgcn_global_load_lds((const unsigned*)((const char*)(gbase) + (voff)[_i]), (PG8_LAS unsigned*)(lds + (bufoff) + ldsw + _i * 8192), 16, 0, 0); } while (0)
; #define PG8_LDA(dst, b, h) do { _Pragma("unroll") for (int m = 0; m < 4; ++m) _Pragma("unroll") for (int k = 0; k < 2; ++k) dst[m][k] = *(const PG8_LAS bf16x8*)(lds + PG8_SA(b, h) + aoff + m * 2048 + k * 1024); } while (0)
; #define PG8_MMA(ai, bj, At, Bt) do { __builtin_amdgcn_s_setprio(1); _Pragma("unroll") for (int m = 0; m < 4; ++m) _Pragma("unroll") for (int n = 0; n < 2; ++n) _Pragma("unroll") for (int k = 0; k < 2; ++k) \
;         acc[ai][bj][m][n] = __builtin_amdgcn_mfma_f32_16x16x32_bf16(Bt[n][k], At[m][k], acc[ai][bj][m][n], 0, 0, 0); __builtin_amdgcn_s_setprio(0); } while (0)
; #define PG8_WAIT_V(n) asm volatile("s_waitcnt vmcnt(" #n ")" ::: "memory")
; #define PG8_WAIT_L(n) asm volatile("s_waitcnt lgkmcnt(" #n ")" ::: "memory")
; #define PG8_BAR __builtin_amdgcn_s_barrier()
; #define PG8_SCHED __builtin_amdgcn_sched_barrier(0)
; template <class Epi, class Sched>
; __device__ __forceinline__ void gemm_phase(PG8_LAS unsigned char* lds, const Gemm g, const Sched& S, const Epi& E) {
;     ...
;             PG8_LDA(At, 1, 1); PG8_STAGE(PG8_SB(1, 0), b3, voffB); PG8_STAGE(PG8_SB(1, 1), b3 + hstepB, voffB); PG8_STAGE(PG8_SA(1, 0), a3, voffA);
;             PG8_WAIT_V(8); PG8_WAIT_L(0); PG8_BAR; PG8_MMA(1, 0, At, B0); PG8_MMA(1, 1, At, B1); PG8_BAR; PG8_SCHED;
;         }
;         if (wr == 0) PG8_BAR;
	s_add_i32 s9, s9, s80
	v_lshl_add_u64 v[140:141], v[140:141], 0, s[22:23]
	s_mov_b32 m0, s9
	ds_read_b128 v[186:189], v145 offset:49152
	ds_read_b128 v[190:193], v145 offset:50176
	ds_read_b128 v[194:197], v145 offset:51200
	ds_read_b128 v[198:201], v145 offset:52224
	ds_read_b128 v[202:205], v145 offset:53248
	ds_read_b128 v[216:219], v145 offset:54272
	ds_read_b128 v[220:223], v145 offset:55296
	ds_read_b128 v[224:227], v145 offset:56320
	global_load_lds_dwordx4 v[140:141], off
	s_add_i32 m0, s9, 0x2000
	s_add_u32 s10, s38, 0x80080
	v_lshl_add_u64 v[140:141], v[168:169], 0, s[22:23]
	s_addc_u32 s11, s39, 0
	s_add_i32 s9, s57, s80
	global_load_lds_dwordx4 v[140:141], off
	v_lshl_add_u64 v[140:141], s[10:11], 0, v[0:1]
	s_mov_b32 m0, s9
	s_nop 0
	global_load_lds_dwordx4 v[140:141], off
	v_lshl_add_u64 v[140:141], s[10:11], 0, v[130:131]
	s_add_i32 m0, s9, 0x2000
	s_nop 0
	global_load_lds_dwordx4 v[140:141], off
	v_lshl_add_u64 v[140:141], v[228:229], 0, s[22:23]
	s_mov_b32 m0, s20
	s_nop 0
	global_load_lds_dwordx4 v[140:141], off
	v_lshl_add_u64 v[140:141], v[230:231], 0, s[22:23]
	s_mov_b32 m0, s86
	s_nop 0
	global_load_lds_dwordx4 v[140:141], off
	s_waitcnt vmcnt(8)
	s_waitcnt lgkmcnt(0)
	s_barrier
	s_setprio 1
	s_waitcnt lgkmcnt(0)
	v_mfma_f32_16x16x32_bf16 v[54:57], v[146:149], v[186:189], v[54:57]
	v_mfma_f32_16x16x32_bf16 v[50:53], v[154:157], v[186:189], v[50:53]
	v_mfma_f32_16x16x32_bf16 v[46:49], v[146:149], v[194:197], v[46:49]
	v_mfma_f32_16x16x32_bf16 v[38:41], v[154:157], v[194:197], v[38:41]
	v_mfma_f32_16x16x32_bf16 v[22:25], v[146:149], v[202:205], v[22:25]
	v_mfma_f32_16x16x32_bf16 v[18:21], v[154:157], v[202:205], v[18:21]
	v_mfma_f32_16x16x32_bf16 v[14:17], v[146:149], v[220:223], v[14:17]
	v_mfma_f32_16x16x32_bf16 v[6:9], v[154:157], v[220:223], v[6:9]
	v_mfma_f32_16x16x32_bf16 v[54:57], v[150:153], v[190:193], v[54:57]
	v_mfma_f32_16x16x32_bf16 v[50:53], v[158:161], v[190:193], v[50:53]
	v_mfma_f32_16x16x32_bf16 v[46:49], v[150:153], v[198:201], v[46:49]
	v_mfma_f32_16x16x32_bf16 v[38:41], v[158:161], v[198:201], v[38:41]
	v_mfma_f32_16x16x32_bf16 v[22:25], v[150:153], v[216:219], v[22:25]
	v_mfma_f32_16x16x32_bf16 v[18:21], v[158:161], v[216:219], v[18:21]
	v_mfma_f32_16x16x32_bf16 v[14:17], v[150:153], v[224:227], v[14:17]
	v_mfma_f32_16x16x32_bf16 v[6:9], v[158:161], v[224:227], v[6:9]
	v_mfma_f32_16x16x32_bf16 v[62:65], v[170:173], v[186:189], v[62:65]
	v_mfma_f32_16x16x32_bf16 v[58:61], v[178:181], v[186:189], v[58:61]
	v_mfma_f32_16x16x32_bf16 v[42:45], v[170:173], v[194:197], v[42:45]
	v_mfma_f32_16x16x32_bf16 v[34:37], v[178:181], v[194:197], v[34:37]
	v_mfma_f32_16x16x32_bf16 v[30:33], v[170:173], v[202:205], v[30:33]
	v_mfma_f32_16x16x32_bf16 v[26:29], v[178:181], v[202:205], v[26:29]
	v_mfma_f32_16x16x32_bf16 v[10:13], v[170:173], v[220:223], v[10:13]
	v_mfma_f32_16x16x32_bf16 v[2:5], v[178:181], v[220:223], v[2:5]
	v_mfma_f32_16x16x32_bf16 v[62:65], v[174:177], v[190:193], v[62:65]
	v_mfma_f32_16x16x32_bf16 v[58:61], v[182:185], v[190:193], v[58:61]
	v_mfma_f32_16x16x32_bf16 v[42:45], v[174:177], v[198:201], v[42:45]
	v_mfma_f32_16x16x32_bf16 v[34:37], v[182:185], v[198:201], v[34:37]
	v_mfma_f32_16x16x32_bf16 v[30:33], v[174:177], v[216:219], v[30:33]
	v_mfma_f32_16x16x32_bf16 v[26:29], v[182:185], v[216:219], v[26:29]
	v_mfma_f32_16x16x32_bf16 v[10:13], v[174:177], v[224:227], v[10:13]
	v_mfma_f32_16x16x32_bf16 v[2:5], v[182:185], v[224:227], v[2:5]
	s_setprio 0
	s_barrier
	s_add_i32 s8, s8, 2
	s_add_u32 s28, s28, 0x100
	s_addc_u32 s29, s29, 0
	s_add_u32 s6, s6, 0x100
	s_addc_u32 s7, s7, 0
	s_cmp_gt_u32 s8, 29
	s_cbranch_scc0 .LBB0_24
	s_and_b64 vcc, exec, s[50:51]
	s_cbranch_vccz .LBB0_27
	s_barrier

; #define PG8_STAGE(bufoff, gbase, voff) do { _Pragma("unroll") for (int _i = 0; _i < 2; ++_i) \
;         __builtin_amdgcn_global_load_lds((const unsigned*)((const char*)(gbase) + (voff)[_i]), (PG8_LAS unsigned*)(lds + (bufoff) + ldsw + _i * 8192), 16, 0, 0); } while (0)
; #define PG8_LDA(dst, b, h) do { _Pragma("unroll") for (int m = 0; m < 4; ++m) _Pragma("unroll") for (int k = 0; k < 2; ++k) dst[m][k] = *(const PG8_LAS bf16x8*)(lds + PG8_SA(b, h) + aoff + m * 2048 + k * 1024); } while (0)
; #define PG8_LDB(dst, b, h) do { _Pragma("unroll") for (int n = 0; n < 2; ++n) _Pragma("unroll") for (int k = 0; k < 2; ++k) dst[n][k] = *(const PG8_LAS bf16x8*)(lds + PG8_SB(b, h) + boff + n * 2048 + k * 1024); } while (0)
; #define PG8_MMA(ai, bj, At, Bt) do { __builtin_amdgcn_s_setprio(1); _Pragma("unroll") for (int m = 0; m < 4; ++m) _Pragma("unroll") for (int n = 0; n < 2; ++n) _Pragma("unroll") for (int k = 0; k < 2; ++k) \
;         acc[ai][bj][m][n] = __builtin_amdgcn_mfma_f32_16x16x32_bf16(Bt[n][k], At[m][k], acc[ai][bj][m][n], 0, 0, 0); __builtin_amdgcn_s_setprio(0); } while (0)
; #define PG8_WAIT_V(n) asm volatile("s_waitcnt vmcnt(" #n ")" ::: "memory")
; #define PG8_WAIT_L(n) asm volatile("s_waitcnt lgkmcnt(" #n ")" ::: "memory")
; #define PG8_BAR __builtin_amdgcn_s_barrier()
; #define PG8_SCHED __builtin_amdgcn_sched_barrier(0)
; template <class Epi, class Sched>
; __device__ __forceinline__ void gemm_phase(PG8_LAS unsigned char* lds, const Gemm g, const Sched& S, const Epi& E) {
;     ...
;         for (int t = 0; t < nt; t += 2) {
;             const bool last = (t == nt - 2);
;             const char* a1 = cA + (size_t)(t + 1) * kstep;
;             const char* a2 = last ? nA : cA + (size_t)(t + 2) * kstep; const char* b2 = last ? nB : cB + (size_t)(t + 2) * kstep;
;             const char* a3 = a2 + kstep; const char* b3 = b2 + kstep;
;             PG8_LDB(B0, 0, 0); PG8_LDB(B1, 0, 1); PG8_SCHED; PG8_LDA(At, 0, 0); PG8_STAGE(PG8_SA(1, 1), a1 + hstepA, voffA);
;             PG8_WAIT_V(8); PG8_WAIT_L(0); PG8_BAR; PG8_MMA(0, 0, At, B0); PG8_MMA(0, 1, At, B1); PG8_BAR; PG8_SCHED;
;             PG8_LDA(At, 0, 1); PG8_STAGE(PG8_SB(0, 0), b2, voffB); PG8_STAGE(PG8_SB(0, 1), b2 + hstepB, voffB); PG8_STAGE(PG8_SA(0, 0), a2, voffA);
;             PG8_WAIT_V(8); PG8_WAIT_L(0); PG8_BAR; PG8_MMA(1, 0, At, B0); PG8_MMA(1, 1, At, B1); PG8_BAR; PG8_SCHED;
.LBB0_60:
	s_add_i32 s8, s7, 2
	s_add_u32 s9, s28, 0x80
	s_addc_u32 s10, s29, 0
	s_add_i32 s44, 0, 0x10000
	s_cmp_eq_u32 s91, s7
	s_cselect_b32 s39, s13, s10
	s_cselect_b32 s38, s12, s9
	s_cselect_b32 s11, s67, s6
	s_cselect_b32 s10, s66, s5
	s_add_i32 s7, 0, 0x14000
	v_add_u32_e32 v142, s44, v192
	v_add_u32_e32 v158, s7, v192
	ds_read_b128 v[130:133], v142
	ds_read_b128 v[134:137], v142 offset:1024
	ds_read_b128 v[138:141], v142 offset:2048
	ds_read_b128 v[142:145], v142 offset:3072
	ds_read_b128 v[146:149], v158
	ds_read_b128 v[150:153], v158 offset:1024
	ds_read_b128 v[154:157], v158 offset:2048
	ds_read_b128 v[158:161], v158 offset:3072
	v_lshl_add_u64 v[168:169], s[28:29], 0, v[176:177]
	s_add_i32 m0, s84, 0xc000
	ds_read_b128 v[180:183], v194
	ds_read_b128 v[184:187], v194 offset:1024
	ds_read_b128 v[188:191], v194 offset:2048
	ds_read_b128 v[196:199], v194 offset:3072
	ds_read_b128 v[200:203], v194 offset:4096
	ds_read_b128 v[216:219], v194 offset:5120
	ds_read_b128 v[220:223], v194 offset:6144
	ds_read_b128 v[224:227], v194 offset:7168
	global_load_lds_dwordx4 v[168:169], off
	v_lshl_add_u64 v[168:169], s[28:29], 0, v[178:179]
	s_add_i32 m0, s84, 0xe000
	s_nop 0
	global_load_lds_dwordx4 v[168:169], off
	s_waitcnt vmcnt(8)
	s_waitcnt lgkmcnt(0)
	s_barrier
	s_setprio 1
	s_waitcnt lgkmcnt(0)
	v_mfma_f32_16x16x32_bf16 v[126:129], v[130:133], v[180:183], v[126:129]
	v_mfma_f32_16x16x32_bf16 v[122:125], v[138:141], v[180:183], v[122:125]
	v_mfma_f32_16x16x32_bf16 v[114:117], v[130:133], v[188:191], v[114:117]
	v_mfma_f32_16x16x32_bf16 v[106:109], v[138:141], v[188:191], v[106:109]
	v_mfma_f32_16x16x32_bf16 v[94:97], v[130:133], v[200:203], v[94:97]
	v_mfma_f32_16x16x32_bf16 v[90:93], v[138:141], v[200:203], v[90:93]
	v_mfma_f32_16x16x32_bf16 v[82:85], v[130:133], v[220:223], v[82:85]
	v_mfma_f32_16x16x32_bf16 v[74:77], v[138:141], v[220:223], v[74:77]
	v_mfma_f32_16x16x32_bf16 v[126:129], v[134:137], v[184:187], v[126:129]
	v_mfma_f32_16x16x32_bf16 v[122:125], v[142:145], v[184:187], v[122:125]
	v_mfma_f32_16x16x32_bf16 v[114:117], v[134:137], v[196:199], v[114:117]
	v_mfma_f32_16x16x32_bf16 v[106:109], v[142:145], v[196:199], v[106:109]
	v_mfma_f32_16x16x32_bf16 v[94:97], v[134:137], v[216:219], v[94:97]
	v_mfma_f32_16x16x32_bf16 v[90:93], v[142:145], v[216:219], v[90:93]
	v_mfma_f32_16x16x32_bf16 v[82:85], v[134:137], v[224:227], v[82:85]
	v_mfma_f32_16x16x32_bf16 v[74:77], v[142:145], v[224:227], v[74:77]
	v_mfma_f32_16x16x32_bf16 v[118:121], v[146:149], v[180:183], v[118:121]
	v_mfma_f32_16x16x32_bf16 v[110:113], v[154:157], v[180:183], v[110:113]
	v_mfma_f32_16x16x32_bf16 v[102:105], v[146:149], v[188:191], v[102:105]
	v_mfma_f32_16x16x32_bf16 v[98:101], v[154:157], v[188:191], v[98:101]
	v_mfma_f32_16x16x32_bf16 v[86:89], v[146:149], v[200:203], v[86:89]
	v_mfma_f32_16x16x32_bf16 v[78:81], v[154:157], v[200:203], v[78:81]
	v_mfma_f32_16x16x32_bf16 v[70:73], v[146:149], v[220:223], v[70:73]
	v_mfma_f32_16x16x32_bf16 v[66:69], v[154:157], v[220:223], v[66:69]
	v_mfma_f32_16x16x32_bf16 v[118:121], v[150:153], v[184:187], v[118:121]
	v_mfma_f32_16x16x32_bf16 v[110:113], v[158:161], v[184:187], v[110:113]
	v_mfma_f32_16x16x32_bf16 v[102:105], v[150:153], v[196:199], v[102:105]
	v_mfma_f32_16x16x32_bf16 v[98:101], v[158:161], v[196:199], v[98:101]
	v_mfma_f32_16x16x32_bf16 v[86:89], v[150:153], v[216:219], v[86:89]
	v_mfma_f32_16x16x32_bf16 v[78:81], v[158:161], v[216:219], v[78:81]
	v_mfma_f32_16x16x32_bf16 v[70:73], v[150:153], v[224:227], v[70:73]
	v_mfma_f32_16x16x32_bf16 v[66:69], v[158:161], v[224:227], v[66:69]
	s_setprio 0
	s_barrier
	s_add_i32 s9, s44, s83
	v_lshl_add_u64 v[168:169], s[10:11], 0, v[0:1]
	s_mov_b32 m0, s9
	ds_read_b128 v[180:183], v194 offset:16384
	ds_read_b128 v[184:187], v194 offset:17408
	ds_read_b128 v[188:191], v194 offset:18432
	ds_read_b128 v[196:199], v194 offset:19456
	ds_read_b128 v[200:203], v194 offset:20480
	ds_read_b128 v[216:219], v194 offset:21504
	ds_read_b128 v[220:223], v194 offset:22528
	ds_read_b128 v[224:227], v194 offset:23552
	global_load_lds_dwordx4 v[168:169], off
	s_add_i32 m0, s9, 0x2000
	v_lshl_add_u64 v[204:205], s[10:11], 0, v[174:175]
	s_add_u32 s10, s10, s20
	s_addc_u32 s11, s11, 0
	s_add_i32 s7, s7, s83
	global_load_lds_dwordx4 v[204:205], off
	v_lshl_add_u64 v[228:229], s[10:11], 0, v[0:1]
	s_mov_b32 m0, s7
	v_lshl_add_u64 v[230:231], s[10:11], 0, v[174:175]
	global_load_lds_dwordx4 v[228:229], off
	s_add_i32 m0, s7, 0x2000
	v_lshl_add_u64 v[232:233], s[38:39], 0, v[170:171]
	global_load_lds_dwordx4 v[230:231], off
	s_mov_b32 m0, s84
	v_lshl_add_u64 v[234:235], s[38:39], 0, v[172:173]
	global_load_lds_dwordx4 v[232:233], off
	s_mov_b32 m0, s85
	s_nop 0
	global_load_lds_dwordx4 v[234:235], off
	s_waitcnt vmcnt(8)
	s_waitcnt lgkmcnt(0)
	s_barrier
; #define PG8_STAGE(bufoff, gbase, voff) do { _Pragma("unroll") for (int _i = 0; _i < 2; ++_i) \
;         __builtin_amdgcn_global_load_lds((const unsigned*)((const char*)(gbase) + (voff)[_i]), (PG8_LAS unsigned*)(lds + (bufoff) + ldsw + _i * 8192), 16, 0, 0); } while (0)
; #define PG8_LDA(dst, b, h) do { _Pragma("unroll") for (int m = 0; m < 4; ++m) _Pragma("unroll") for (int k = 0; k < 2; ++k) dst[m][k] = *(const PG8_LAS bf16x8*)(lds + PG8_SA(b, h) + aoff + m * 2048 + k * 1024); } while (0)
; #define PG8_LDB(dst, b, h) do { _Pragma("unroll") for (int n = 0; n < 2; ++n) _Pragma("unroll") for (int k = 0; k < 2; ++k) dst[n][k] = *(const PG8_LAS bf16x8*)(lds + PG8_SB(b, h) + boff + n * 2048 + k * 1024); } while (0)
; #define PG8_MMA(ai, bj, At, Bt) do { __builtin_amdgcn_s_setprio(1); _Pragma("unroll") for (int m = 0; m < 4; ++m) _Pragma("unroll") for (int n = 0; n < 2; ++n) _Pragma("unroll") for (int k = 0; k < 2; ++k) \
;         acc[ai][bj][m][n] = __builtin_amdgcn_mfma_f32_16x16x32_bf16(Bt[n][k], At[m][k], acc[ai][bj][m][n], 0, 0, 0); __builtin_amdgcn_s_setprio(0); } while (0)
; #define PG8_WAIT_V(n) asm volatile("s_waitcnt vmcnt(" #n ")" ::: "memory")
; #define PG8_WAIT_L(n) asm volatile("s_waitcnt lgkmcnt(" #n ")" ::: "memory")
; #define PG8_BAR __builtin_amdgcn_s_barrier()
; #define PG8_SCHED __builtin_amdgcn_sched_barrier(0)
; template <class Epi, class Sched>
; __device__ __forceinline__ void gemm_phase(PG8_LAS unsigned char* lds, const Gemm g, const Sched& S, const Epi& E) {
;     ...
;             PG8_WAIT_V(8); PG8_WAIT_L(0); PG8_BAR; PG8_MMA(1, 0, At, B0); PG8_MMA(1, 1, At, B1); PG8_BAR; PG8_SCHED;
;             PG8_LDB(B0, 1, 0); PG8_LDB(B1, 1, 1); PG8_SCHED; PG8_LDA(At, 1, 0); PG8_STAGE(PG8_SA(0, 1), a2 + hstepA, voffA);
;             PG8_WAIT_V(8); PG8_WAIT_L(0); PG8_BAR; PG8_MMA(0, 0, At, B0); PG8_MMA(0, 1, At, B1); PG8_BAR; PG8_SCHED;
;             PG8_LDA(At, 1, 1); PG8_STAGE(PG8_SB(1, 0), b3, voffB); PG8_STAGE(PG8_SB(1, 1), b3 + hstepB, voffB); PG8_STAGE(PG8_SA(1, 0), a3, voffA);
;             PG8_WAIT_V(8); PG8_WAIT_L(0); PG8_BAR; PG8_MMA(1, 0, At, B0); PG8_MMA(1, 1, At, B1); PG8_BAR; PG8_SCHED;
	s_setprio 1
	s_waitcnt lgkmcnt(0)
	v_mfma_f32_16x16x32_bf16 v[62:65], v[130:133], v[180:183], v[62:65]
	v_mfma_f32_16x16x32_bf16 v[58:61], v[138:141], v[180:183], v[58:61]
	v_mfma_f32_16x16x32_bf16 v[50:53], v[130:133], v[188:191], v[50:53]
	v_mfma_f32_16x16x32_bf16 v[42:45], v[138:141], v[188:191], v[42:45]
	v_mfma_f32_16x16x32_bf16 v[30:33], v[130:133], v[200:203], v[30:33]
	v_mfma_f32_16x16x32_bf16 v[26:29], v[138:141], v[200:203], v[26:29]
	v_mfma_f32_16x16x32_bf16 v[18:21], v[130:133], v[220:223], v[18:21]
	v_mfma_f32_16x16x32_bf16 v[10:13], v[138:141], v[220:223], v[10:13]
	v_mfma_f32_16x16x32_bf16 v[62:65], v[134:137], v[184:187], v[62:65]
	v_mfma_f32_16x16x32_bf16 v[58:61], v[142:145], v[184:187], v[58:61]
	v_mfma_f32_16x16x32_bf16 v[50:53], v[134:137], v[196:199], v[50:53]
	v_mfma_f32_16x16x32_bf16 v[42:45], v[142:145], v[196:199], v[42:45]
	v_mfma_f32_16x16x32_bf16 v[30:33], v[134:137], v[216:219], v[30:33]
	v_mfma_f32_16x16x32_bf16 v[26:29], v[142:145], v[216:219], v[26:29]
	v_mfma_f32_16x16x32_bf16 v[18:21], v[134:137], v[224:227], v[18:21]
	v_mfma_f32_16x16x32_bf16 v[10:13], v[142:145], v[224:227], v[10:13]
	v_mfma_f32_16x16x32_bf16 v[54:57], v[146:149], v[180:183], v[54:57]
	v_mfma_f32_16x16x32_bf16 v[46:49], v[154:157], v[180:183], v[46:49]
	v_mfma_f32_16x16x32_bf16 v[38:41], v[146:149], v[188:191], v[38:41]
	v_mfma_f32_16x16x32_bf16 v[34:37], v[154:157], v[188:191], v[34:37]
	v_mfma_f32_16x16x32_bf16 v[22:25], v[146:149], v[200:203], v[22:25]
	v_mfma_f32_16x16x32_bf16 v[14:17], v[154:157], v[200:203], v[14:17]
	v_mfma_f32_16x16x32_bf16 v[6:9], v[146:149], v[220:223], v[6:9]
	v_mfma_f32_16x16x32_bf16 v[2:5], v[154:157], v[220:223], v[2:5]
	v_mfma_f32_16x16x32_bf16 v[54:57], v[150:153], v[184:187], v[54:57]
	v_mfma_f32_16x16x32_bf16 v[46:49], v[158:161], v[184:187], v[46:49]
	v_mfma_f32_16x16x32_bf16 v[38:41], v[150:153], v[196:199], v[38:41]
	v_mfma_f32_16x16x32_bf16 v[34:37], v[158:161], v[196:199], v[34:37]
	v_mfma_f32_16x16x32_bf16 v[22:25], v[150:153], v[216:219], v[22:25]
	v_mfma_f32_16x16x32_bf16 v[14:17], v[158:161], v[216:219], v[14:17]
	v_mfma_f32_16x16x32_bf16 v[6:9], v[150:153], v[224:227], v[6:9]
	v_mfma_f32_16x16x32_bf16 v[2:5], v[158:161], v[224:227], v[2:5]
	s_setprio 0
	s_barrier
	s_add_i32 s7, 0, 0x18000
	s_add_i32 s9, 0, 0x1c000
	v_add_u32_e32 v142, s7, v192
	v_add_u32_e32 v158, s9, v192
	ds_read_b128 v[130:133], v142
	ds_read_b128 v[134:137], v142 offset:1024
	ds_read_b128 v[138:141], v142 offset:2048
	ds_read_b128 v[142:145], v142 offset:3072
	ds_read_b128 v[146:149], v158
	ds_read_b128 v[150:153], v158 offset:1024
	ds_read_b128 v[154:157], v158 offset:2048
	ds_read_b128 v[158:161], v158 offset:3072
	s_add_u32 s10, s38, s20
	s_addc_u32 s11, s39, 0
	s_mov_b32 m0, s86
	v_lshl_add_u64 v[236:237], s[10:11], 0, v[170:171]
	ds_read_b128 v[180:183], v194 offset:32768
	ds_read_b128 v[184:187], v194 offset:33792
	ds_read_b128 v[188:191], v194 offset:34816
	ds_read_b128 v[196:199], v194 offset:35840
	ds_read_b128 v[200:203], v194 offset:36864
	ds_read_b128 v[216:219], v194 offset:37888
	ds_read_b128 v[220:223], v194 offset:38912
	ds_read_b128 v[224:227], v194 offset:39936
	global_load_lds_dwordx4 v[236:237], off
	v_lshl_add_u64 v[236:237], s[10:11], 0, v[172:173]
	s_mov_b32 m0, s87
	s_nop 0
	global_load_lds_dwordx4 v[236:237], off
	s_waitcnt vmcnt(8)
	s_waitcnt lgkmcnt(0)
	s_barrier
	s_setprio 1
	s_waitcnt lgkmcnt(0)
	v_mfma_f32_16x16x32_bf16 v[126:129], v[130:133], v[180:183], v[126:129]
	v_mfma_f32_16x16x32_bf16 v[122:125], v[138:141], v[180:183], v[122:125]
	v_mfma_f32_16x16x32_bf16 v[114:117], v[130:133], v[188:191], v[114:117]
	v_mfma_f32_16x16x32_bf16 v[106:109], v[138:141], v[188:191], v[106:109]
	v_mfma_f32_16x16x32_bf16 v[94:97], v[130:133], v[200:203], v[94:97]
	v_mfma_f32_16x16x32_bf16 v[90:93], v[138:141], v[200:203], v[90:93]
	v_mfma_f32_16x16x32_bf16 v[82:85], v[130:133], v[220:223], v[82:85]
	v_mfma_f32_16x16x32_bf16 v[74:77], v[138:141], v[220:223], v[74:77]
	v_mfma_f32_16x16x32_bf16 v[126:129], v[134:137], v[184:187], v[126:129]
	v_mfma_f32_16x16x32_bf16 v[122:125], v[142:145], v[184:187], v[122:125]
	v_mfma_f32_16x16x32_bf16 v[114:117], v[134:137], v[196:199], v[114:117]
	v_mfma_f32_16x16x32_bf16 v[106:109], v[142:145], v[196:199], v[106:109]
	v_mfma_f32_16x16x32_bf16 v[94:97], v[134:137], v[216:219], v[94:97]
	v_mfma_f32_16x16x32_bf16 v[90:93], v[142:145], v[216:219], v[90:93]
	v_mfma_f32_16x16x32_bf16 v[82:85], v[134:137], v[224:227], v[82:85]
	v_mfma_f32_16x16x32_bf16 v[74:77], v[142:145], v[224:227], v[74:77]
	v_mfma_f32_16x16x32_bf16 v[118:121], v[146:149], v[180:183], v[118:121]
	v_mfma_f32_16x16x32_bf16 v[110:113], v[154:157], v[180:183], v[110:113]
	v_mfma_f32_16x16x32_bf16 v[102:105], v[146:149], v[188:191], v[102:105]
	v_mfma_f32_16x16x32_bf16 v[98:101], v[154:157], v[188:191], v[98:101]
	v_mfma_f32_16x16x32_bf16 v[86:89], v[146:149], v[200:203], v[86:89]
	v_mfma_f32_16x16x32_bf16 v[78:81], v[154:157], v[200:203], v[78:81]
	v_mfma_f32_16x16x32_bf16 v[70:73], v[146:149], v[220:223], v[70:73]
	v_mfma_f32_16x16x32_bf16 v[66:69], v[154:157], v[220:223], v[66:69]
	v_mfma_f32_16x16x32_bf16 v[118:121], v[150:153], v[184:187], v[118:121]
	v_mfma_f32_16x16x32_bf16 v[110:113], v[158:161], v[184:187], v[110:113]
	v_mfma_f32_16x16x32_bf16 v[102:105], v[150:153], v[196:199], v[102:105]
	v_mfma_f32_16x16x32_bf16 v[98:101], v[158:161], v[196:199], v[98:101]
	v_mfma_f32_16x16x32_bf16 v[86:89], v[150:153], v[216:219], v[86:89]
	v_mfma_f32_16x16x32_bf16 v[78:81], v[158:161], v[216:219], v[78:81]
	v_mfma_f32_16x16x32_bf16 v[70:73], v[150:153], v[224:227], v[70:73]
	v_mfma_f32_16x16x32_bf16 v[66:69], v[158:161], v[224:227], v[66:69]
	s_setprio 0
	s_barrier
; #define PG8_STAGE(bufoff, gbase, voff) do { _Pragma("unroll") for (int _i = 0; _i < 2; ++_i) \
;         __builtin_amdgcn_global_load_lds((const unsigned*)((const char*)(gbase) + (voff)[_i]), (PG8_LAS unsigned*)(lds + (bufoff) + ldsw + _i * 8192), 16, 0, 0); } while (0)
; #define PG8_LDA(dst, b, h) do { _Pragma("unroll") for (int m = 0; m < 4; ++m) _Pragma("unroll") for (int k = 0; k < 2; ++k) dst[m][k] = *(const PG8_LAS bf16x8*)(lds + PG8_SA(b, h) + aoff + m * 2048 + k * 1024); } while (0)
; #define PG8_MMA(ai, bj, At, Bt) do { __builtin_amdgcn_s_setprio(1); _Pragma("unroll") for (int m = 0; m < 4; ++m) _Pragma("unroll") for (int n = 0; n < 2; ++n) _Pragma("unroll") for (int k = 0; k < 2; ++k) \
;         acc[ai][bj][m][n] = __builtin_amdgcn_mfma_f32_16x16x32_bf16(Bt[n][k], At[m][k], acc[ai][bj][m][n], 0, 0, 0); __builtin_amdgcn_s_setprio(0); } while (0)
; #define PG8_WAIT_V(n) asm volatile("s_waitcnt vmcnt(" #n ")" ::: "memory")
; #define PG8_WAIT_L(n) asm volatile("s_waitcnt lgkmcnt(" #n ")" ::: "memory")
; #define PG8_BAR __builtin_amdgcn_s_barrier()
; #define PG8_SCHED __builtin_amdgcn_sched_barrier(0)
; template <class Epi, class Sched>
; __device__ __forceinline__ void gemm_phase(PG8_LAS unsigned char* lds, const Gemm g, const Sched& S, const Epi& E) {
;     ...
;             PG8_LDA(At, 1, 1); PG8_STAGE(PG8_SB(1, 0), b3, voffB); PG8_STAGE(PG8_SB(1, 1), b3 + hstepB, voffB); PG8_STAGE(PG8_SA(1, 0), a3, voffA);
;             PG8_WAIT_V(8); PG8_WAIT_L(0); PG8_BAR; PG8_MMA(1, 0, At, B0); PG8_MMA(1, 1, At, B1); PG8_BAR; PG8_SCHED;
;         }
;         if (wr == 0) PG8_BAR;
	s_add_i32 s7, s7, s83
	v_lshl_add_u64 v[168:169], v[168:169], 0, s[22:23]
	s_mov_b32 m0, s7
	ds_read_b128 v[180:183], v194 offset:49152
	ds_read_b128 v[184:187], v194 offset:50176
	ds_read_b128 v[188:191], v194 offset:51200
	ds_read_b128 v[196:199], v194 offset:52224
	ds_read_b128 v[200:203], v194 offset:53248
	ds_read_b128 v[216:219], v194 offset:54272
	ds_read_b128 v[220:223], v194 offset:55296
	ds_read_b128 v[224:227], v194 offset:56320
	global_load_lds_dwordx4 v[168:169], off
	v_lshl_add_u64 v[168:169], v[204:205], 0, s[22:23]
	s_add_i32 m0, s7, 0x2000
	s_add_i32 s7, s9, s83
	global_load_lds_dwordx4 v[168:169], off
	v_lshl_add_u64 v[168:169], v[228:229], 0, s[22:23]
	s_mov_b32 m0, s7
	s_nop 0
	global_load_lds_dwordx4 v[168:169], off
	v_lshl_add_u64 v[168:169], v[230:231], 0, s[22:23]
	s_add_i32 m0, s7, 0x2000
	s_nop 0
	global_load_lds_dwordx4 v[168:169], off
	v_lshl_add_u64 v[168:169], v[232:233], 0, s[22:23]
	s_mov_b32 m0, s88
	s_nop 0
	global_load_lds_dwordx4 v[168:169], off
	v_lshl_add_u64 v[168:169], v[234:235], 0, s[22:23]
	s_mov_b32 m0, s89
	s_nop 0
	global_load_lds_dwordx4 v[168:169], off
	s_waitcnt vmcnt(8)
	s_waitcnt lgkmcnt(0)
	s_barrier
	s_setprio 1
	s_waitcnt lgkmcnt(0)
	v_mfma_f32_16x16x32_bf16 v[62:65], v[130:133], v[180:183], v[62:65]
	v_mfma_f32_16x16x32_bf16 v[58:61], v[138:141], v[180:183], v[58:61]
	v_mfma_f32_16x16x32_bf16 v[50:53], v[130:133], v[188:191], v[50:53]
	v_mfma_f32_16x16x32_bf16 v[42:45], v[138:141], v[188:191], v[42:45]
	v_mfma_f32_16x16x32_bf16 v[30:33], v[130:133], v[200:203], v[30:33]
	v_mfma_f32_16x16x32_bf16 v[26:29], v[138:141], v[200:203], v[26:29]
	v_mfma_f32_16x16x32_bf16 v[18:21], v[130:133], v[220:223], v[18:21]
	v_mfma_f32_16x16x32_bf16 v[10:13], v[138:141], v[220:223], v[10:13]
	v_mfma_f32_16x16x32_bf16 v[62:65], v[134:137], v[184:187], v[62:65]
	v_mfma_f32_16x16x32_bf16 v[58:61], v[142:145], v[184:187], v[58:61]
	v_mfma_f32_16x16x32_bf16 v[50:53], v[134:137], v[196:199], v[50:53]
	v_mfma_f32_16x16x32_bf16 v[42:45], v[142:145], v[196:199], v[42:45]
	v_mfma_f32_16x16x32_bf16 v[30:33], v[134:137], v[216:219], v[30:33]
	v_mfma_f32_16x16x32_bf16 v[26:29], v[142:145], v[216:219], v[26:29]
	v_mfma_f32_16x16x32_bf16 v[18:21], v[134:137], v[224:227], v[18:21]
	v_mfma_f32_16x16x32_bf16 v[10:13], v[142:145], v[224:227], v[10:13]
	v_mfma_f32_16x16x32_bf16 v[54:57], v[146:149], v[180:183], v[54:57]
	v_mfma_f32_16x16x32_bf16 v[46:49], v[154:157], v[180:183], v[46:49]
	v_mfma_f32_16x16x32_bf16 v[38:41], v[146:149], v[188:191], v[38:41]
	v_mfma_f32_16x16x32_bf16 v[34:37], v[154:157], v[188:191], v[34:37]
	v_mfma_f32_16x16x32_bf16 v[22:25], v[146:149], v[200:203], v[22:25]
	v_mfma_f32_16x16x32_bf16 v[14:17], v[154:157], v[200:203], v[14:17]
	v_mfma_f32_16x16x32_bf16 v[6:9], v[146:149], v[220:223], v[6:9]
	v_mfma_f32_16x16x32_bf16 v[2:5], v[154:157], v[220:223], v[2:5]
	v_mfma_f32_16x16x32_bf16 v[54:57], v[150:153], v[184:187], v[54:57]
	v_mfma_f32_16x16x32_bf16 v[46:49], v[158:161], v[184:187], v[46:49]
	v_mfma_f32_16x16x32_bf16 v[38:41], v[150:153], v[196:199], v[38:41]
	v_mfma_f32_16x16x32_bf16 v[34:37], v[158:161], v[196:199], v[34:37]
	v_mfma_f32_16x16x32_bf16 v[22:25], v[150:153], v[216:219], v[22:25]
	v_mfma_f32_16x16x32_bf16 v[14:17], v[158:161], v[216:219], v[14:17]
	v_mfma_f32_16x16x32_bf16 v[6:9], v[150:153], v[224:227], v[6:9]
	v_mfma_f32_16x16x32_bf16 v[2:5], v[158:161], v[224:227], v[2:5]
	s_setprio 0
	s_barrier
	s_add_u32 s28, s28, 0x100
	s_addc_u32 s29, s29, 0
	s_add_u32 s5, s5, 0x100
	s_addc_u32 s6, s6, 0
	s_cmp_ge_u32 s8, s90
	s_mov_b32 s7, s8
	s_cbranch_scc0 .LBB0_60
	s_and_b64 vcc, exec, s[64:65]
	s_cbranch_vccz .LBB0_63
	s_barrier

; #define PG8_STAGE(bufoff, gbase, voff) do { _Pragma("unroll") for (int _i = 0; _i < 2; ++_i) \
;         __builtin_amdgcn_global_load_lds((const unsigned*)((const char*)(gbase) + (voff)[_i]), (PG8_LAS unsigned*)(lds + (bufoff) + ldsw + _i * 8192), 16, 0, 0); } while (0)
; #define PG8_LDA(dst, b, h) do { _Pragma("unroll") for (int m = 0; m < 4; ++m) _Pragma("unroll") for (int k = 0; k < 2; ++k) dst[m][k] = *(const PG8_LAS bf16x8*)(lds + PG8_SA(b, h) + aoff + m * 2048 + k * 1024); } while (0)
; #define PG8_LDB(dst, b, h) do { _Pragma("unroll") for (int n = 0; n < 2; ++n) _Pragma("unroll") for (int k = 0; k < 2; ++k) dst[n][k] = *(const PG8_LAS bf16x8*)(lds + PG8_SB(b, h) + boff + n * 2048 + k * 1024); } while (0)
; #define PG8_MMA(ai, bj, At, Bt) do { __builtin_amdgcn_s_setprio(1); _Pragma("unroll") for (int m = 0; m < 4; ++m) _Pragma("unroll") for (int n = 0; n < 2; ++n) _Pragma("unroll") for (int k = 0; k < 2; ++k) \
;         acc[ai][bj][m][n] = __builtin_amdgcn_mfma_f32_16x16x32_bf16(Bt[n][k], At[m][k], acc[ai][bj][m][n], 0, 0, 0); __builtin_amdgcn_s_setprio(0); } while (0)
; #define PG8_WAIT_V(n) asm volatile("s_waitcnt vmcnt(" #n ")" ::: "memory")
; #define PG8_WAIT_L(n) asm volatile("s_waitcnt lgkmcnt(" #n ")" ::: "memory")
; #define PG8_BAR __builtin_amdgcn_s_barrier()
; #define PG8_SCHED __builtin_amdgcn_sched_barrier(0)
; template <class Epi, class Sched>
; __device__ __forceinline__ void gemm_phase(PG8_LAS unsigned char* lds, const Gemm g, const Sched& S, const Epi& E) {
;     ...
;         for (int t = 0; t < nt; t += 2) {
;             const bool last = (t == nt - 2);
;             const char* a1 = cA + (size_t)(t + 1) * kstep;
;             const char* a2 = last ? nA : cA + (size_t)(t + 2) * kstep; const char* b2 = last ? nB : cB + (size_t)(t + 2) * kstep;
;             const char* a3 = a2 + kstep; const char* b3 = b2 + kstep;
;             PG8_LDB(B0, 0, 0); PG8_LDB(B1, 0, 1); PG8_SCHED; PG8_LDA(At, 0, 0); PG8_STAGE(PG8_SA(1, 1), a1 + hstepA, voffA);
;             PG8_WAIT_V(8); PG8_WAIT_L(0); PG8_BAR; PG8_MMA(0, 0, At, B0); PG8_MMA(0, 1, At, B1); PG8_BAR; PG8_SCHED;
;             PG8_LDA(At, 0, 1); PG8_STAGE(PG8_SB(0, 0), b2, voffB); PG8_STAGE(PG8_SB(0, 1), b2 + hstepB, voffB); PG8_STAGE(PG8_SA(0, 0), a2, voffA);
;             PG8_WAIT_V(8); PG8_WAIT_L(0); PG8_BAR; PG8_MMA(1, 0, At, B0); PG8_MMA(1, 1, At, B1); PG8_BAR; PG8_SCHED;
.LBB0_132:
	s_add_u32 s10, s28, 0xfff80080
	s_addc_u32 s11, s29, -1
	s_add_i32 s76, 0, 0x10000
	s_cmp_eq_u32 s9, 12
	s_cselect_b32 vcc_hi, s67, s11
	s_cselect_b32 vcc_lo, s97, s10
	v_add_u32_e32 v0, s76, v216
	s_cselect_b32 s43, s65, s8
	s_cselect_b32 s42, s6, s7
	s_add_i32 s57, 0, 0x14000
	ds_read_b128 v[66:69], v0
	ds_read_b128 v[78:81], v0 offset:1024
	ds_read_b128 v[90:93], v0 offset:2048
	ds_read_b128 v[102:105], v0 offset:3072
	v_add_u32_e32 v0, s57, v216
	ds_read_b128 v[146:149], v0
	ds_read_b128 v[150:153], v0 offset:1024
	ds_read_b128 v[154:157], v0 offset:2048
	ds_read_b128 v[158:161], v0 offset:3072
	v_lshl_add_u64 v[168:169], s[28:29], 0, v[178:179]
	s_add_i32 m0, s88, 0xc000
	ds_read_b128 v[182:185], v218
	ds_read_b128 v[186:189], v218 offset:1024
	ds_read_b128 v[190:193], v218 offset:2048
	ds_read_b128 v[194:197], v218 offset:3072
	ds_read_b128 v[198:201], v218 offset:4096
	ds_read_b128 v[202:205], v218 offset:5120
	ds_read_b128 v[220:223], v218 offset:6144
	ds_read_b128 v[224:227], v218 offset:7168
	global_load_lds_dwordx4 v[168:169], off
	v_lshl_add_u64 v[168:169], s[28:29], 0, v[180:181]
	s_add_i32 m0, s88, 0xe000
	s_nop 0
	global_load_lds_dwordx4 v[168:169], off
	s_waitcnt vmcnt(8)
	s_waitcnt lgkmcnt(0)
	s_barrier
	s_setprio 1
	s_waitcnt lgkmcnt(0)
	v_mfma_f32_16x16x32_bf16 v[142:145], v[66:69], v[182:185], v[142:145]
	v_mfma_f32_16x16x32_bf16 v[138:141], v[90:93], v[182:185], v[138:141]
	v_mfma_f32_16x16x32_bf16 v[134:137], v[66:69], v[190:193], v[134:137]
	v_mfma_f32_16x16x32_bf16 v[130:133], v[90:93], v[190:193], v[130:133]
	v_mfma_f32_16x16x32_bf16 v[126:129], v[66:69], v[198:201], v[126:129]
	v_mfma_f32_16x16x32_bf16 v[122:125], v[90:93], v[198:201], v[122:125]
	v_mfma_f32_16x16x32_bf16 v[118:121], v[66:69], v[220:223], v[118:121]
	v_mfma_f32_16x16x32_bf16 v[114:117], v[90:93], v[220:223], v[114:117]
	v_mfma_f32_16x16x32_bf16 v[142:145], v[78:81], v[186:189], v[142:145]
	v_mfma_f32_16x16x32_bf16 v[138:141], v[102:105], v[186:189], v[138:141]
	v_mfma_f32_16x16x32_bf16 v[134:137], v[78:81], v[194:197], v[134:137]
	v_mfma_f32_16x16x32_bf16 v[130:133], v[102:105], v[194:197], v[130:133]
	v_mfma_f32_16x16x32_bf16 v[126:129], v[78:81], v[202:205], v[126:129]
	v_mfma_f32_16x16x32_bf16 v[122:125], v[102:105], v[202:205], v[122:125]
	v_mfma_f32_16x16x32_bf16 v[118:121], v[78:81], v[224:227], v[118:121]
	v_mfma_f32_16x16x32_bf16 v[114:117], v[102:105], v[224:227], v[114:117]
	v_mfma_f32_16x16x32_bf16 v[62:65], v[146:149], v[182:185], v[62:65]
	v_mfma_f32_16x16x32_bf16 v[58:61], v[154:157], v[182:185], v[58:61]
	v_mfma_f32_16x16x32_bf16 v[54:57], v[146:149], v[190:193], v[54:57]
	v_mfma_f32_16x16x32_bf16 v[50:53], v[154:157], v[190:193], v[50:53]
	v_mfma_f32_16x16x32_bf16 v[46:49], v[146:149], v[198:201], v[46:49]
	v_mfma_f32_16x16x32_bf16 v[42:45], v[154:157], v[198:201], v[42:45]
	v_mfma_f32_16x16x32_bf16 v[38:41], v[146:149], v[220:223], v[38:41]
	v_mfma_f32_16x16x32_bf16 v[34:37], v[154:157], v[220:223], v[34:37]
	v_mfma_f32_16x16x32_bf16 v[62:65], v[150:153], v[186:189], v[62:65]
	v_mfma_f32_16x16x32_bf16 v[58:61], v[158:161], v[186:189], v[58:61]
	v_mfma_f32_16x16x32_bf16 v[54:57], v[150:153], v[194:197], v[54:57]
	v_mfma_f32_16x16x32_bf16 v[50:53], v[158:161], v[194:197], v[50:53]
	v_mfma_f32_16x16x32_bf16 v[46:49], v[150:153], v[202:205], v[46:49]
	v_mfma_f32_16x16x32_bf16 v[42:45], v[158:161], v[202:205], v[42:45]
	v_mfma_f32_16x16x32_bf16 v[38:41], v[150:153], v[224:227], v[38:41]
	v_mfma_f32_16x16x32_bf16 v[34:37], v[158:161], v[224:227], v[34:37]
	s_setprio 0
	s_barrier
	s_add_i32 s10, s76, s87
	v_lshl_add_u64 v[168:169], s[42:43], 0, v[174:175]
	s_mov_b32 m0, s10
	ds_read_b128 v[182:185], v218 offset:16384
	ds_read_b128 v[186:189], v218 offset:17408
	ds_read_b128 v[190:193], v218 offset:18432
	ds_read_b128 v[194:197], v218 offset:19456
	ds_read_b128 v[198:201], v218 offset:20480
	ds_read_b128 v[202:205], v218 offset:21504
	ds_read_b128 v[220:223], v218 offset:22528
	ds_read_b128 v[224:227], v218 offset:23552
	global_load_lds_dwordx4 v[168:169], off
	s_add_i32 m0, s10, 0x2000
	s_add_u32 s10, s42, 0x80000
	v_lshl_add_u64 v[228:229], s[42:43], 0, v[170:171]
	s_addc_u32 s11, s43, 0
	s_add_i32 s57, s57, s87
	global_load_lds_dwordx4 v[228:229], off
	v_lshl_add_u64 v[230:231], s[10:11], 0, v[174:175]
	s_mov_b32 m0, s57
	v_lshl_add_u64 v[232:233], vcc, 0, v[172:173]
	global_load_lds_dwordx4 v[230:231], off
	v_lshl_add_u64 v[230:231], s[10:11], 0, v[170:171]
	s_add_i32 m0, s57, 0x2000
	s_nop 0
	global_load_lds_dwordx4 v[230:231], off
	v_lshl_add_u64 v[230:231], vcc, 0, v[176:177]
	s_mov_b32 m0, s88
	s_nop 0
	global_load_lds_dwordx4 v[230:231], off
	s_mov_b32 m0, s89
	s_nop 0
	global_load_lds_dwordx4 v[232:233], off
	s_waitcnt vmcnt(8)
	s_waitcnt lgkmcnt(0)
	s_barrier
; #define PG8_STAGE(bufoff, gbase, voff) do { _Pragma("unroll") for (int _i = 0; _i < 2; ++_i) \
;         __builtin_amdgcn_global_load_lds((const unsigned*)((const char*)(gbase) + (voff)[_i]), (PG8_LAS unsigned*)(lds + (bufoff) + ldsw + _i * 8192), 16, 0, 0); } while (0)
; #define PG8_LDA(dst, b, h) do { _Pragma("unroll") for (int m = 0; m < 4; ++m) _Pragma("unroll") for (int k = 0; k < 2; ++k) dst[m][k] = *(const PG8_LAS bf16x8*)(lds + PG8_SA(b, h) + aoff + m * 2048 + k * 1024); } while (0)
; #define PG8_LDB(dst, b, h) do { _Pragma("unroll") for (int n = 0; n < 2; ++n) _Pragma("unroll") for (int k = 0; k < 2; ++k) dst[n][k] = *(const PG8_LAS bf16x8*)(lds + PG8_SB(b, h) + boff + n * 2048 + k * 1024); } while (0)
; #define PG8_MMA(ai, bj, At, Bt) do { __builtin_amdgcn_s_setprio(1); _Pragma("unroll") for (int m = 0; m < 4; ++m) _Pragma("unroll") for (int n = 0; n < 2; ++n) _Pragma("unroll") for (int k = 0; k < 2; ++k) \
;         acc[ai][bj][m][n] = __builtin_amdgcn_mfma_f32_16x16x32_bf16(Bt[n][k], At[m][k], acc[ai][bj][m][n], 0, 0, 0); __builtin_amdgcn_s_setprio(0); } while (0)
; #define PG8_WAIT_V(n) asm volatile("s_waitcnt vmcnt(" #n ")" ::: "memory")
; #define PG8_WAIT_L(n) asm volatile("s_waitcnt lgkmcnt(" #n ")" ::: "memory")
; #define PG8_BAR __builtin_amdgcn_s_barrier()
; #define PG8_SCHED __builtin_amdgcn_sched_barrier(0)
; template <class Epi, class Sched>
; __device__ __forceinline__ void gemm_phase(PG8_LAS unsigned char* lds, const Gemm g, const Sched& S, const Epi& E) {
;     ...
;             PG8_WAIT_V(8); PG8_WAIT_L(0); PG8_BAR; PG8_MMA(1, 0, At, B0); PG8_MMA(1, 1, At, B1); PG8_BAR; PG8_SCHED;
;             PG8_LDB(B0, 1, 0); PG8_LDB(B1, 1, 1); PG8_SCHED; PG8_LDA(At, 1, 0); PG8_STAGE(PG8_SA(0, 1), a2 + hstepA, voffA);
;             PG8_WAIT_V(8); PG8_WAIT_L(0); PG8_BAR; PG8_MMA(0, 0, At, B0); PG8_MMA(0, 1, At, B1); PG8_BAR; PG8_SCHED;
	s_setprio 1
	s_waitcnt lgkmcnt(0)
	v_mfma_f32_16x16x32_bf16 v[110:113], v[66:69], v[182:185], v[110:113]
	v_mfma_f32_16x16x32_bf16 v[106:109], v[90:93], v[182:185], v[106:109]
	v_mfma_f32_16x16x32_bf16 v[98:101], v[66:69], v[190:193], v[98:101]
	v_mfma_f32_16x16x32_bf16 v[94:97], v[90:93], v[190:193], v[94:97]
	v_mfma_f32_16x16x32_bf16 v[86:89], v[66:69], v[198:201], v[86:89]
	v_mfma_f32_16x16x32_bf16 v[82:85], v[90:93], v[198:201], v[82:85]
	v_mfma_f32_16x16x32_bf16 v[70:73], v[90:93], v[220:223], v[70:73]
	v_mfma_f32_16x16x32_bf16 v[110:113], v[78:81], v[186:189], v[110:113]
	v_mfma_f32_16x16x32_bf16 v[106:109], v[102:105], v[186:189], v[106:109]
	v_mfma_f32_16x16x32_bf16 v[98:101], v[78:81], v[194:197], v[98:101]
	v_mfma_f32_16x16x32_bf16 v[94:97], v[102:105], v[194:197], v[94:97]
	v_mfma_f32_16x16x32_bf16 v[86:89], v[78:81], v[202:205], v[86:89]
	v_mfma_f32_16x16x32_bf16 v[82:85], v[102:105], v[202:205], v[82:85]
	v_mfma_f32_16x16x32_bf16 v[66:69], v[66:69], v[220:223], v[74:77]
	v_mfma_f32_16x16x32_bf16 v[70:73], v[102:105], v[224:227], v[70:73]
	v_mfma_f32_16x16x32_bf16 v[66:69], v[78:81], v[224:227], v[66:69]
	v_mfma_f32_16x16x32_bf16 v[30:33], v[146:149], v[182:185], v[30:33]
	v_mfma_f32_16x16x32_bf16 v[26:29], v[154:157], v[182:185], v[26:29]
	v_mfma_f32_16x16x32_bf16 v[22:25], v[146:149], v[190:193], v[22:25]
	v_mfma_f32_16x16x32_bf16 v[18:21], v[154:157], v[190:193], v[18:21]
	v_mfma_f32_16x16x32_bf16 v[14:17], v[146:149], v[198:201], v[14:17]
	v_mfma_f32_16x16x32_bf16 v[10:13], v[154:157], v[198:201], v[10:13]
	v_mfma_f32_16x16x32_bf16 v[6:9], v[146:149], v[220:223], v[6:9]
	v_mfma_f32_16x16x32_bf16 v[2:5], v[154:157], v[220:223], v[2:5]
	v_mfma_f32_16x16x32_bf16 v[30:33], v[150:153], v[186:189], v[30:33]
	v_mfma_f32_16x16x32_bf16 v[26:29], v[158:161], v[186:189], v[26:29]
	v_mfma_f32_16x16x32_bf16 v[22:25], v[150:153], v[194:197], v[22:25]
	v_mfma_f32_16x16x32_bf16 v[18:21], v[158:161], v[194:197], v[18:21]
	v_mfma_f32_16x16x32_bf16 v[14:17], v[150:153], v[202:205], v[14:17]
	v_mfma_f32_16x16x32_bf16 v[10:13], v[158:161], v[202:205], v[10:13]
	v_mfma_f32_16x16x32_bf16 v[6:9], v[150:153], v[224:227], v[6:9]
	v_mfma_f32_16x16x32_bf16 v[2:5], v[158:161], v[224:227], v[2:5]
	s_setprio 0
	s_barrier
	s_add_i32 s57, 0, 0x18000
	v_add_u32_e32 v0, s57, v216
	s_add_i32 s76, 0, 0x1c000
	ds_read_b128 v[74:77], v0
	ds_read_b128 v[78:81], v0 offset:1024
	ds_read_b128 v[90:93], v0 offset:2048
	ds_read_b128 v[102:105], v0 offset:3072
	v_add_u32_e32 v0, s76, v216
	ds_read_b128 v[146:149], v0
	ds_read_b128 v[150:153], v0 offset:1024
	ds_read_b128 v[154:157], v0 offset:2048
	ds_read_b128 v[158:161], v0 offset:3072
	s_add_u32 s10, vcc_lo, 0x80000
	s_addc_u32 s11, vcc_hi, 0
	s_mov_b32 m0, s90
	v_lshl_add_u64 v[234:235], s[10:11], 0, v[176:177]
	ds_read_b128 v[182:185], v218 offset:32768
	ds_read_b128 v[186:189], v218 offset:33792
	ds_read_b128 v[190:193], v218 offset:34816
	ds_read_b128 v[194:197], v218 offset:35840
	ds_read_b128 v[198:201], v218 offset:36864
	ds_read_b128 v[202:205], v218 offset:37888
	ds_read_b128 v[220:223], v218 offset:38912
	ds_read_b128 v[224:227], v218 offset:39936
	global_load_lds_dwordx4 v[234:235], off
	v_lshl_add_u64 v[234:235], s[10:11], 0, v[172:173]
	s_mov_b32 m0, s91
	s_nop 0
	global_load_lds_dwordx4 v[234:235], off
	s_waitcnt vmcnt(8)
	s_waitcnt lgkmcnt(0)
	s_barrier
	s_setprio 1
	s_waitcnt lgkmcnt(0)
	v_mfma_f32_16x16x32_bf16 v[142:145], v[74:77], v[182:185], v[142:145]
	v_mfma_f32_16x16x32_bf16 v[138:141], v[90:93], v[182:185], v[138:141]
	v_mfma_f32_16x16x32_bf16 v[134:137], v[74:77], v[190:193], v[134:137]
	v_mfma_f32_16x16x32_bf16 v[130:133], v[90:93], v[190:193], v[130:133]
	v_mfma_f32_16x16x32_bf16 v[126:129], v[74:77], v[198:201], v[126:129]
	v_mfma_f32_16x16x32_bf16 v[122:125], v[90:93], v[198:201], v[122:125]
	v_mfma_f32_16x16x32_bf16 v[118:121], v[74:77], v[220:223], v[118:121]
	v_mfma_f32_16x16x32_bf16 v[114:117], v[90:93], v[220:223], v[114:117]
	v_mfma_f32_16x16x32_bf16 v[142:145], v[78:81], v[186:189], v[142:145]
	v_mfma_f32_16x16x32_bf16 v[138:141], v[102:105], v[186:189], v[138:141]
	v_mfma_f32_16x16x32_bf16 v[134:137], v[78:81], v[194:197], v[134:137]
	v_mfma_f32_16x16x32_bf16 v[130:133], v[102:105], v[194:197], v[130:133]
	v_mfma_f32_16x16x32_bf16 v[126:129], v[78:81], v[202:205], v[126:129]
	v_mfma_f32_16x16x32_bf16 v[122:125], v[102:105], v[202:205], v[122:125]
	v_mfma_f32_16x16x32_bf16 v[118:121], v[78:81], v[224:227], v[118:121]
	v_mfma_f32_16x16x32_bf16 v[114:117], v[102:105], v[224:227], v[114:117]
	v_mfma_f32_16x16x32_bf16 v[62:65], v[146:149], v[182:185], v[62:65]
	v_mfma_f32_16x16x32_bf16 v[58:61], v[154:157], v[182:185], v[58:61]
	v_mfma_f32_16x16x32_bf16 v[54:57], v[146:149], v[190:193], v[54:57]
	v_mfma_f32_16x16x32_bf16 v[50:53], v[154:157], v[190:193], v[50:53]
	v_mfma_f32_16x16x32_bf16 v[46:49], v[146:149], v[198:201], v[46:49]
	v_mfma_f32_16x16x32_bf16 v[42:45], v[154:157], v[198:201], v[42:45]
	v_mfma_f32_16x16x32_bf16 v[38:41], v[146:149], v[220:223], v[38:41]
	v_mfma_f32_16x16x32_bf16 v[34:37], v[154:157], v[220:223], v[34:37]
	v_mfma_f32_16x16x32_bf16 v[62:65], v[150:153], v[186:189], v[62:65]
	v_mfma_f32_16x16x32_bf16 v[58:61], v[158:161], v[186:189], v[58:61]
	v_mfma_f32_16x16x32_bf16 v[54:57], v[150:153], v[194:197], v[54:57]
	v_mfma_f32_16x16x32_bf16 v[50:53], v[158:161], v[194:197], v[50:53]
	v_mfma_f32_16x16x32_bf16 v[46:49], v[150:153], v[202:205], v[46:49]
	v_mfma_f32_16x16x32_bf16 v[42:45], v[158:161], v[202:205], v[42:45]
	v_mfma_f32_16x16x32_bf16 v[38:41], v[150:153], v[224:227], v[38:41]
	v_mfma_f32_16x16x32_bf16 v[34:37], v[158:161], v[224:227], v[34:37]
	s_setprio 0
	s_barrier
; #define PG8_STAGE(bufoff, gbase, voff) do { _Pragma("unroll") for (int _i = 0; _i < 2; ++_i) \
;         __builtin_amdgcn_global_load_lds((const unsigned*)((const char*)(gbase) + (voff)[_i]), (PG8_LAS unsigned*)(lds + (bufoff) + ldsw + _i * 8192), 16, 0, 0); } while (0)
; #define PG8_LDA(dst, b, h) do { _Pragma("unroll") for (int m = 0; m < 4; ++m) _Pragma("unroll") for (int k = 0; k < 2; ++k) dst[m][k] = *(const PG8_LAS bf16x8*)(lds + PG8_SA(b, h) + aoff + m * 2048 + k * 1024); } while (0)
; #define PG8_MMA(ai, bj, At, Bt) do { __builtin_amdgcn_s_setprio(1); _Pragma("unroll") for (int m = 0; m < 4; ++m) _Pragma("unroll") for (int n = 0; n < 2; ++n) _Pragma("unroll") for (int k = 0; k < 2; ++k) \
;         acc[ai][bj][m][n] = __builtin_amdgcn_mfma_f32_16x16x32_bf16(Bt[n][k], At[m][k], acc[ai][bj][m][n], 0, 0, 0); __builtin_amdgcn_s_setprio(0); } while (0)
; #define PG8_WAIT_V(n) asm volatile("s_waitcnt vmcnt(" #n ")" ::: "memory")
; #define PG8_WAIT_L(n) asm volatile("s_waitcnt lgkmcnt(" #n ")" ::: "memory")
; #define PG8_BAR __builtin_amdgcn_s_barrier()
; #define PG8_SCHED __builtin_amdgcn_sched_barrier(0)
; template <class Epi, class Sched>
; __device__ __forceinline__ void gemm_phase(PG8_LAS unsigned char* lds, const Gemm g, const Sched& S, const Epi& E) {
;     ...
;             PG8_LDA(At, 1, 1); PG8_STAGE(PG8_SB(1, 0), b3, voffB); PG8_STAGE(PG8_SB(1, 1), b3 + hstepB, voffB); PG8_STAGE(PG8_SA(1, 0), a3, voffA);
;             PG8_WAIT_V(8); PG8_WAIT_L(0); PG8_BAR; PG8_MMA(1, 0, At, B0); PG8_MMA(1, 1, At, B1); PG8_BAR; PG8_SCHED;
;         }
;         if (wr == 0) PG8_BAR;
	s_add_i32 s10, s57, s87
	v_lshl_add_u64 v[168:169], v[168:169], 0, s[22:23]
	s_mov_b32 m0, s10
	ds_read_b128 v[182:185], v218 offset:49152
	ds_read_b128 v[186:189], v218 offset:50176
	ds_read_b128 v[190:193], v218 offset:51200
	ds_read_b128 v[194:197], v218 offset:52224
	ds_read_b128 v[198:201], v218 offset:53248
	ds_read_b128 v[202:205], v218 offset:54272
	ds_read_b128 v[220:223], v218 offset:55296
	ds_read_b128 v[224:227], v218 offset:56320
	global_load_lds_dwordx4 v[168:169], off
	s_add_i32 m0, s10, 0x2000
	s_add_u32 s10, s42, 0x80080
	v_lshl_add_u64 v[168:169], v[228:229], 0, s[22:23]
	s_addc_u32 s11, s43, 0
	s_add_i32 s42, s76, s87
	global_load_lds_dwordx4 v[168:169], off
	v_lshl_add_u64 v[168:169], s[10:11], 0, v[174:175]
	s_mov_b32 m0, s42
	s_nop 0
	global_load_lds_dwordx4 v[168:169], off
	v_lshl_add_u64 v[168:169], s[10:11], 0, v[170:171]
	s_add_i32 m0, s42, 0x2000
	s_nop 0
	global_load_lds_dwordx4 v[168:169], off
	v_lshl_add_u64 v[168:169], v[230:231], 0, s[22:23]
	s_mov_b32 m0, s94
	s_nop 0
	global_load_lds_dwordx4 v[168:169], off
	v_lshl_add_u64 v[168:169], v[232:233], 0, s[22:23]
	s_mov_b32 m0, s95
	s_nop 0
	global_load_lds_dwordx4 v[168:169], off
	s_waitcnt vmcnt(8)
	s_waitcnt lgkmcnt(0)
	s_barrier
	s_setprio 1
	s_waitcnt lgkmcnt(0)
	v_mfma_f32_16x16x32_bf16 v[66:69], v[74:77], v[220:223], v[66:69]
	v_mfma_f32_16x16x32_bf16 v[110:113], v[74:77], v[182:185], v[110:113]
	v_mfma_f32_16x16x32_bf16 v[106:109], v[90:93], v[182:185], v[106:109]
	v_mfma_f32_16x16x32_bf16 v[98:101], v[74:77], v[190:193], v[98:101]
	v_mfma_f32_16x16x32_bf16 v[94:97], v[90:93], v[190:193], v[94:97]
	v_mfma_f32_16x16x32_bf16 v[86:89], v[74:77], v[198:201], v[86:89]
	v_mfma_f32_16x16x32_bf16 v[82:85], v[90:93], v[198:201], v[82:85]
	v_mfma_f32_16x16x32_bf16 v[74:77], v[78:81], v[224:227], v[66:69]
	v_mfma_f32_16x16x32_bf16 v[66:69], v[90:93], v[220:223], v[70:73]
	v_mfma_f32_16x16x32_bf16 v[110:113], v[78:81], v[186:189], v[110:113]
	v_mfma_f32_16x16x32_bf16 v[106:109], v[102:105], v[186:189], v[106:109]
	v_mfma_f32_16x16x32_bf16 v[98:101], v[78:81], v[194:197], v[98:101]
	v_mfma_f32_16x16x32_bf16 v[94:97], v[102:105], v[194:197], v[94:97]
	v_mfma_f32_16x16x32_bf16 v[86:89], v[78:81], v[202:205], v[86:89]
	v_mfma_f32_16x16x32_bf16 v[82:85], v[102:105], v[202:205], v[82:85]
	v_mfma_f32_16x16x32_bf16 v[70:73], v[102:105], v[224:227], v[66:69]
	v_mfma_f32_16x16x32_bf16 v[30:33], v[146:149], v[182:185], v[30:33]
	v_mfma_f32_16x16x32_bf16 v[26:29], v[154:157], v[182:185], v[26:29]
	v_mfma_f32_16x16x32_bf16 v[22:25], v[146:149], v[190:193], v[22:25]
	v_mfma_f32_16x16x32_bf16 v[18:21], v[154:157], v[190:193], v[18:21]
	v_mfma_f32_16x16x32_bf16 v[14:17], v[146:149], v[198:201], v[14:17]
	v_mfma_f32_16x16x32_bf16 v[10:13], v[154:157], v[198:201], v[10:13]
	v_mfma_f32_16x16x32_bf16 v[6:9], v[146:149], v[220:223], v[6:9]
	v_mfma_f32_16x16x32_bf16 v[2:5], v[154:157], v[220:223], v[2:5]
	v_mfma_f32_16x16x32_bf16 v[30:33], v[150:153], v[186:189], v[30:33]
	v_mfma_f32_16x16x32_bf16 v[26:29], v[158:161], v[186:189], v[26:29]
	v_mfma_f32_16x16x32_bf16 v[22:25], v[150:153], v[194:197], v[22:25]
	v_mfma_f32_16x16x32_bf16 v[18:21], v[158:161], v[194:197], v[18:21]
	v_mfma_f32_16x16x32_bf16 v[14:17], v[150:153], v[202:205], v[14:17]
	v_mfma_f32_16x16x32_bf16 v[10:13], v[158:161], v[202:205], v[10:13]
	v_mfma_f32_16x16x32_bf16 v[6:9], v[150:153], v[224:227], v[6:9]
	v_mfma_f32_16x16x32_bf16 v[2:5], v[158:161], v[224:227], v[2:5]
	s_setprio 0
	s_barrier
	s_add_i32 s9, s9, 2
	s_add_u32 s28, s28, 0x100
	s_addc_u32 s29, s29, 0
	s_add_u32 s7, s7, 0x100
	s_addc_u32 s8, s8, 0
	s_cmp_gt_u32 s9, 13
	s_cbranch_scc0 .LBB0_132
	s_and_b64 vcc, exec, s[60:61]
	s_cbranch_vccz .LBB0_135
	s_barrier

; #define PG8_STAGE(bufoff, gbase, voff) do { _Pragma("unroll") for (int _i = 0; _i < 2; ++_i) \
;         __builtin_amdgcn_global_load_lds((const unsigned*)((const char*)(gbase) + (voff)[_i]), (PG8_LAS unsigned*)(lds + (bufoff) + ldsw + _i * 8192), 16, 0, 0); } while (0)
; #define PG8_LDA(dst, b, h) do { _Pragma("unroll") for (int m = 0; m < 4; ++m) _Pragma("unroll") for (int k = 0; k < 2; ++k) dst[m][k] = *(const PG8_LAS bf16x8*)(lds + PG8_SA(b, h) + aoff + m * 2048 + k * 1024); } while (0)
; #define PG8_LDB(dst, b, h) do { _Pragma("unroll") for (int n = 0; n < 2; ++n) _Pragma("unroll") for (int k = 0; k < 2; ++k) dst[n][k] = *(const PG8_LAS bf16x8*)(lds + PG8_SB(b, h) + boff + n * 2048 + k * 1024); } while (0)
; #define PG8_MMA(ai, bj, At, Bt) do { __builtin_amdgcn_s_setprio(1); _Pragma("unroll") for (int m = 0; m < 4; ++m) _Pragma("unroll") for (int n = 0; n < 2; ++n) _Pragma("unroll") for (int k = 0; k < 2; ++k) \
;         acc[ai][bj][m][n] = __builtin_amdgcn_mfma_f32_16x16x32_bf16(Bt[n][k], At[m][k], acc[ai][bj][m][n], 0, 0, 0); __builtin_amdgcn_s_setprio(0); } while (0)
; #define PG8_WAIT_V(n) asm volatile("s_waitcnt vmcnt(" #n ")" ::: "memory")
; #define PG8_WAIT_L(n) asm volatile("s_waitcnt lgkmcnt(" #n ")" ::: "memory")
; #define PG8_BAR __builtin_amdgcn_s_barrier()
; #define PG8_SCHED __builtin_amdgcn_sched_barrier(0)
; template <class Epi, class Sched>
; __device__ __forceinline__ void gemm_phase(PG8_LAS unsigned char* lds, const Gemm g, const Sched& S, const Epi& E) {
;     ...
;         for (int t = 0; t < nt; t += 2) {
;             const bool last = (t == nt - 2);
;             const char* a1 = cA + (size_t)(t + 1) * kstep;
;             const char* a2 = last ? nA : cA + (size_t)(t + 2) * kstep; const char* b2 = last ? nB : cB + (size_t)(t + 2) * kstep;
;             const char* a3 = a2 + kstep; const char* b3 = b2 + kstep;
;             PG8_LDB(B0, 0, 0); PG8_LDB(B1, 0, 1); PG8_SCHED; PG8_LDA(At, 0, 0); PG8_STAGE(PG8_SA(1, 1), a1 + hstepA, voffA);
;             PG8_WAIT_V(8); PG8_WAIT_L(0); PG8_BAR; PG8_MMA(0, 0, At, B0); PG8_MMA(0, 1, At, B1); PG8_BAR; PG8_SCHED;
;             PG8_LDA(At, 0, 1); PG8_STAGE(PG8_SB(0, 0), b2, voffB); PG8_STAGE(PG8_SB(0, 1), b2 + hstepB, voffB); PG8_STAGE(PG8_SA(0, 0), a2, voffA);
;             PG8_WAIT_V(8); PG8_WAIT_L(0); PG8_BAR; PG8_MMA(1, 0, At, B0); PG8_MMA(1, 1, At, B1); PG8_BAR; PG8_SCHED;
.LBB0_197:
	s_add_u32 s9, s28, 0xfffc0080
	s_addc_u32 s10, s29, -1
	s_add_i32 s11, 0, 0x10000
	s_cmp_eq_u32 s8, 12
	s_cselect_b32 s67, s5, s10
	s_cselect_b32 s66, s45, s9
	s_cselect_b32 s65, s43, s88
	s_cselect_b32 s64, s6, s7
	s_add_i32 s9, 0, 0x14000
	v_add_u32_e32 v142, s11, v216
	v_add_u32_e32 v168, s9, v216
	ds_read_b128 v[130:133], v142
	ds_read_b128 v[134:137], v142 offset:1024
	ds_read_b128 v[138:141], v142 offset:2048
	ds_read_b128 v[142:145], v142 offset:3072
	ds_read_b128 v[146:149], v168
	ds_read_b128 v[150:153], v168 offset:1024
	ds_read_b128 v[154:157], v168 offset:2048
	ds_read_b128 v[176:179], v168 offset:3072
	v_lshl_add_u64 v[168:169], s[28:29], 0, v[172:173]
	s_add_i32 m0, s61, 0xc000
	ds_read_b128 v[180:183], v218
	ds_read_b128 v[184:187], v218 offset:1024
	ds_read_b128 v[188:191], v218 offset:2048
	ds_read_b128 v[192:195], v218 offset:3072
	ds_read_b128 v[196:199], v218 offset:4096
	ds_read_b128 v[200:203], v218 offset:5120
	ds_read_b128 v[220:223], v218 offset:6144
	ds_read_b128 v[224:227], v218 offset:7168
	global_load_lds_dwordx4 v[168:169], off
	v_lshl_add_u64 v[168:169], s[28:29], 0, v[174:175]
	s_add_i32 m0, s61, 0xe000
	s_nop 0
	global_load_lds_dwordx4 v[168:169], off
	s_waitcnt vmcnt(8)
	s_waitcnt lgkmcnt(0)
	s_barrier
	s_setprio 1
	s_waitcnt lgkmcnt(0)
	v_mfma_f32_16x16x32_bf16 v[126:129], v[130:133], v[180:183], v[126:129]
	v_mfma_f32_16x16x32_bf16 v[122:125], v[138:141], v[180:183], v[122:125]
	v_mfma_f32_16x16x32_bf16 v[118:121], v[130:133], v[188:191], v[118:121]
	v_mfma_f32_16x16x32_bf16 v[114:117], v[138:141], v[188:191], v[114:117]
	v_mfma_f32_16x16x32_bf16 v[110:113], v[130:133], v[196:199], v[110:113]
	v_mfma_f32_16x16x32_bf16 v[106:109], v[138:141], v[196:199], v[106:109]
	v_mfma_f32_16x16x32_bf16 v[102:105], v[130:133], v[220:223], v[102:105]
	v_mfma_f32_16x16x32_bf16 v[98:101], v[138:141], v[220:223], v[98:101]
	v_mfma_f32_16x16x32_bf16 v[126:129], v[134:137], v[184:187], v[126:129]
	v_mfma_f32_16x16x32_bf16 v[122:125], v[142:145], v[184:187], v[122:125]
	v_mfma_f32_16x16x32_bf16 v[118:121], v[134:137], v[192:195], v[118:121]
	v_mfma_f32_16x16x32_bf16 v[114:117], v[142:145], v[192:195], v[114:117]
	v_mfma_f32_16x16x32_bf16 v[110:113], v[134:137], v[200:203], v[110:113]
	v_mfma_f32_16x16x32_bf16 v[106:109], v[142:145], v[200:203], v[106:109]
	v_mfma_f32_16x16x32_bf16 v[102:105], v[134:137], v[224:227], v[102:105]
	v_mfma_f32_16x16x32_bf16 v[98:101], v[142:145], v[224:227], v[98:101]
	v_mfma_f32_16x16x32_bf16 v[62:65], v[146:149], v[180:183], v[62:65]
	v_mfma_f32_16x16x32_bf16 v[58:61], v[154:157], v[180:183], v[58:61]
	v_mfma_f32_16x16x32_bf16 v[54:57], v[146:149], v[188:191], v[54:57]
	v_mfma_f32_16x16x32_bf16 v[50:53], v[154:157], v[188:191], v[50:53]
	v_mfma_f32_16x16x32_bf16 v[46:49], v[146:149], v[196:199], v[46:49]
	v_mfma_f32_16x16x32_bf16 v[42:45], v[154:157], v[196:199], v[42:45]
	v_mfma_f32_16x16x32_bf16 v[38:41], v[146:149], v[220:223], v[38:41]
	v_mfma_f32_16x16x32_bf16 v[34:37], v[154:157], v[220:223], v[34:37]
	v_mfma_f32_16x16x32_bf16 v[62:65], v[150:153], v[184:187], v[62:65]
	v_mfma_f32_16x16x32_bf16 v[58:61], v[176:179], v[184:187], v[58:61]
	v_mfma_f32_16x16x32_bf16 v[54:57], v[150:153], v[192:195], v[54:57]
	v_mfma_f32_16x16x32_bf16 v[50:53], v[176:179], v[192:195], v[50:53]
	v_mfma_f32_16x16x32_bf16 v[46:49], v[150:153], v[200:203], v[46:49]
	v_mfma_f32_16x16x32_bf16 v[42:45], v[176:179], v[200:203], v[42:45]
	v_mfma_f32_16x16x32_bf16 v[38:41], v[150:153], v[224:227], v[38:41]
	v_mfma_f32_16x16x32_bf16 v[34:37], v[176:179], v[224:227], v[34:37]
	s_setprio 0
	s_barrier
	s_add_i32 s10, s11, s81
	v_lshl_add_u64 v[168:169], s[64:65], 0, v[0:1]
	s_mov_b32 m0, s10
	ds_read_b128 v[180:183], v218 offset:16384
	ds_read_b128 v[184:187], v218 offset:17408
	ds_read_b128 v[188:191], v218 offset:18432
	ds_read_b128 v[192:195], v218 offset:19456
	ds_read_b128 v[196:199], v218 offset:20480
	ds_read_b128 v[200:203], v218 offset:21504
	ds_read_b128 v[220:223], v218 offset:22528
	ds_read_b128 v[224:227], v218 offset:23552
	global_load_lds_dwordx4 v[168:169], off
	s_add_i32 m0, s10, 0x2000
	s_add_u32 s90, s64, 0x40000
	v_lshl_add_u64 v[204:205], s[64:65], 0, v[170:171]
	s_addc_u32 s91, s65, 0
	s_add_i32 s9, s9, s81
	global_load_lds_dwordx4 v[204:205], off
	v_lshl_add_u64 v[228:229], s[90:91], 0, v[0:1]
	s_mov_b32 m0, s9
	v_lshl_add_u64 v[230:231], s[66:67], 0, v[160:161]
	global_load_lds_dwordx4 v[228:229], off
	v_lshl_add_u64 v[228:229], s[90:91], 0, v[170:171]
	s_add_i32 m0, s9, 0x2000
	s_nop 0
	global_load_lds_dwordx4 v[228:229], off
	v_lshl_add_u64 v[228:229], s[66:67], 0, v[158:159]
	s_mov_b32 m0, s61
	s_nop 0
	global_load_lds_dwordx4 v[228:229], off
	s_mov_b32 m0, s82
	s_nop 0
	global_load_lds_dwordx4 v[230:231], off
	s_waitcnt vmcnt(8)
	s_waitcnt lgkmcnt(0)
	s_barrier
; #define PG8_STAGE(bufoff, gbase, voff) do { _Pragma("unroll") for (int _i = 0; _i < 2; ++_i) \
;         __builtin_amdgcn_global_load_lds((const unsigned*)((const char*)(gbase) + (voff)[_i]), (PG8_LAS unsigned*)(lds + (bufoff) + ldsw + _i * 8192), 16, 0, 0); } while (0)
; #define PG8_LDA(dst, b, h) do { _Pragma("unroll") for (int m = 0; m < 4; ++m) _Pragma("unroll") for (int k = 0; k < 2; ++k) dst[m][k] = *(const PG8_LAS bf16x8*)(lds + PG8_SA(b, h) + aoff + m * 2048 + k * 1024); } while (0)
; #define PG8_LDB(dst, b, h) do { _Pragma("unroll") for (int n = 0; n < 2; ++n) _Pragma("unroll") for (int k = 0; k < 2; ++k) dst[n][k] = *(const PG8_LAS bf16x8*)(lds + PG8_SB(b, h) + boff + n * 2048 + k * 1024); } while (0)
; #define PG8_MMA(ai, bj, At, Bt) do { __builtin_amdgcn_s_setprio(1); _Pragma("unroll") for (int m = 0; m < 4; ++m) _Pragma("unroll") for (int n = 0; n < 2; ++n) _Pragma("unroll") for (int k = 0; k < 2; ++k) \
;         acc[ai][bj][m][n] = __builtin_amdgcn_mfma_f32_16x16x32_bf16(Bt[n][k], At[m][k], acc[ai][bj][m][n], 0, 0, 0); __builtin_amdgcn_s_setprio(0); } while (0)
; #define PG8_WAIT_V(n) asm volatile("s_waitcnt vmcnt(" #n ")" ::: "memory")
; #define PG8_WAIT_L(n) asm volatile("s_waitcnt lgkmcnt(" #n ")" ::: "memory")
; #define PG8_BAR __builtin_amdgcn_s_barrier()
; #define PG8_SCHED __builtin_amdgcn_sched_barrier(0)
; template <class Epi, class Sched>
; __device__ __forceinline__ void gemm_phase(PG8_LAS unsigned char* lds, const Gemm g, const Sched& S, const Epi& E) {
;     ...
;             PG8_WAIT_V(8); PG8_WAIT_L(0); PG8_BAR; PG8_MMA(1, 0, At, B0); PG8_MMA(1, 1, At, B1); PG8_BAR; PG8_SCHED;
;             PG8_LDB(B0, 1, 0); PG8_LDB(B1, 1, 1); PG8_SCHED; PG8_LDA(At, 1, 0); PG8_STAGE(PG8_SA(0, 1), a2 + hstepA, voffA);
;             PG8_WAIT_V(8); PG8_WAIT_L(0); PG8_BAR; PG8_MMA(0, 0, At, B0); PG8_MMA(0, 1, At, B1); PG8_BAR; PG8_SCHED;
	s_setprio 1
	s_waitcnt lgkmcnt(0)
	v_mfma_f32_16x16x32_bf16 v[94:97], v[130:133], v[180:183], v[94:97]
	v_mfma_f32_16x16x32_bf16 v[90:93], v[138:141], v[180:183], v[90:93]
	v_mfma_f32_16x16x32_bf16 v[86:89], v[130:133], v[188:191], v[86:89]
	v_mfma_f32_16x16x32_bf16 v[82:85], v[138:141], v[188:191], v[82:85]
	v_mfma_f32_16x16x32_bf16 v[78:81], v[130:133], v[196:199], v[78:81]
	v_mfma_f32_16x16x32_bf16 v[74:77], v[138:141], v[196:199], v[74:77]
	v_mfma_f32_16x16x32_bf16 v[70:73], v[130:133], v[220:223], v[70:73]
	v_mfma_f32_16x16x32_bf16 v[66:69], v[138:141], v[220:223], v[66:69]
	v_mfma_f32_16x16x32_bf16 v[94:97], v[134:137], v[184:187], v[94:97]
	v_mfma_f32_16x16x32_bf16 v[90:93], v[142:145], v[184:187], v[90:93]
	v_mfma_f32_16x16x32_bf16 v[86:89], v[134:137], v[192:195], v[86:89]
	v_mfma_f32_16x16x32_bf16 v[82:85], v[142:145], v[192:195], v[82:85]
	v_mfma_f32_16x16x32_bf16 v[78:81], v[134:137], v[200:203], v[78:81]
	v_mfma_f32_16x16x32_bf16 v[74:77], v[142:145], v[200:203], v[74:77]
	v_mfma_f32_16x16x32_bf16 v[70:73], v[134:137], v[224:227], v[70:73]
	v_mfma_f32_16x16x32_bf16 v[66:69], v[142:145], v[224:227], v[66:69]
	v_mfma_f32_16x16x32_bf16 v[30:33], v[146:149], v[180:183], v[30:33]
	v_mfma_f32_16x16x32_bf16 v[26:29], v[154:157], v[180:183], v[26:29]
	v_mfma_f32_16x16x32_bf16 v[22:25], v[146:149], v[188:191], v[22:25]
	v_mfma_f32_16x16x32_bf16 v[18:21], v[154:157], v[188:191], v[18:21]
	v_mfma_f32_16x16x32_bf16 v[14:17], v[146:149], v[196:199], v[14:17]
	v_mfma_f32_16x16x32_bf16 v[10:13], v[154:157], v[196:199], v[10:13]
	v_mfma_f32_16x16x32_bf16 v[6:9], v[146:149], v[220:223], v[6:9]
	v_mfma_f32_16x16x32_bf16 v[2:5], v[154:157], v[220:223], v[2:5]
	v_mfma_f32_16x16x32_bf16 v[30:33], v[150:153], v[184:187], v[30:33]
	v_mfma_f32_16x16x32_bf16 v[26:29], v[176:179], v[184:187], v[26:29]
	v_mfma_f32_16x16x32_bf16 v[22:25], v[150:153], v[192:195], v[22:25]
	v_mfma_f32_16x16x32_bf16 v[18:21], v[176:179], v[192:195], v[18:21]
	v_mfma_f32_16x16x32_bf16 v[14:17], v[150:153], v[200:203], v[14:17]
	v_mfma_f32_16x16x32_bf16 v[10:13], v[176:179], v[200:203], v[10:13]
	v_mfma_f32_16x16x32_bf16 v[6:9], v[150:153], v[224:227], v[6:9]
	v_mfma_f32_16x16x32_bf16 v[2:5], v[176:179], v[224:227], v[2:5]
	s_setprio 0
	s_barrier
	s_add_i32 s9, 0, 0x18000
	s_add_i32 s10, 0, 0x1c000
	v_add_u32_e32 v142, s9, v216
	v_add_u32_e32 v176, s10, v216
	ds_read_b128 v[130:133], v142
	ds_read_b128 v[134:137], v142 offset:1024
	ds_read_b128 v[138:141], v142 offset:2048
	ds_read_b128 v[142:145], v142 offset:3072
	ds_read_b128 v[146:149], v176
	ds_read_b128 v[150:153], v176 offset:1024
	ds_read_b128 v[154:157], v176 offset:2048
	ds_read_b128 v[176:179], v176 offset:3072
	s_add_u32 s66, s66, 0x40000
	s_addc_u32 s67, s67, 0
	s_mov_b32 m0, s83
	v_lshl_add_u64 v[232:233], s[66:67], 0, v[158:159]
	ds_read_b128 v[180:183], v218 offset:32768
	ds_read_b128 v[184:187], v218 offset:33792
	ds_read_b128 v[188:191], v218 offset:34816
	ds_read_b128 v[192:195], v218 offset:35840
	ds_read_b128 v[196:199], v218 offset:36864
	ds_read_b128 v[200:203], v218 offset:37888
	ds_read_b128 v[220:223], v218 offset:38912
	ds_read_b128 v[224:227], v218 offset:39936
	global_load_lds_dwordx4 v[232:233], off
	v_lshl_add_u64 v[232:233], s[66:67], 0, v[160:161]
	s_mov_b32 m0, s84
	s_nop 0
	global_load_lds_dwordx4 v[232:233], off
	s_waitcnt vmcnt(8)
	s_waitcnt lgkmcnt(0)
	s_barrier
	s_setprio 1
	s_waitcnt lgkmcnt(0)
	v_mfma_f32_16x16x32_bf16 v[126:129], v[130:133], v[180:183], v[126:129]
	v_mfma_f32_16x16x32_bf16 v[122:125], v[138:141], v[180:183], v[122:125]
	v_mfma_f32_16x16x32_bf16 v[118:121], v[130:133], v[188:191], v[118:121]
	v_mfma_f32_16x16x32_bf16 v[114:117], v[138:141], v[188:191], v[114:117]
	v_mfma_f32_16x16x32_bf16 v[110:113], v[130:133], v[196:199], v[110:113]
	v_mfma_f32_16x16x32_bf16 v[106:109], v[138:141], v[196:199], v[106:109]
	v_mfma_f32_16x16x32_bf16 v[102:105], v[130:133], v[220:223], v[102:105]
	v_mfma_f32_16x16x32_bf16 v[98:101], v[138:141], v[220:223], v[98:101]
	v_mfma_f32_16x16x32_bf16 v[126:129], v[134:137], v[184:187], v[126:129]
	v_mfma_f32_16x16x32_bf16 v[122:125], v[142:145], v[184:187], v[122:125]
	v_mfma_f32_16x16x32_bf16 v[118:121], v[134:137], v[192:195], v[118:121]
	v_mfma_f32_16x16x32_bf16 v[114:117], v[142:145], v[192:195], v[114:117]
	v_mfma_f32_16x16x32_bf16 v[110:113], v[134:137], v[200:203], v[110:113]
	v_mfma_f32_16x16x32_bf16 v[106:109], v[142:145], v[200:203], v[106:109]
	v_mfma_f32_16x16x32_bf16 v[102:105], v[134:137], v[224:227], v[102:105]
	v_mfma_f32_16x16x32_bf16 v[98:101], v[142:145], v[224:227], v[98:101]
	v_mfma_f32_16x16x32_bf16 v[62:65], v[146:149], v[180:183], v[62:65]
	v_mfma_f32_16x16x32_bf16 v[58:61], v[154:157], v[180:183], v[58:61]
	v_mfma_f32_16x16x32_bf16 v[54:57], v[146:149], v[188:191], v[54:57]
	v_mfma_f32_16x16x32_bf16 v[50:53], v[154:157], v[188:191], v[50:53]
	v_mfma_f32_16x16x32_bf16 v[46:49], v[146:149], v[196:199], v[46:49]
	v_mfma_f32_16x16x32_bf16 v[42:45], v[154:157], v[196:199], v[42:45]
	v_mfma_f32_16x16x32_bf16 v[38:41], v[146:149], v[220:223], v[38:41]
	v_mfma_f32_16x16x32_bf16 v[34:37], v[154:157], v[220:223], v[34:37]
	v_mfma_f32_16x16x32_bf16 v[62:65], v[150:153], v[184:187], v[62:65]
	v_mfma_f32_16x16x32_bf16 v[58:61], v[176:179], v[184:187], v[58:61]
	v_mfma_f32_16x16x32_bf16 v[54:57], v[150:153], v[192:195], v[54:57]
	v_mfma_f32_16x16x32_bf16 v[50:53], v[176:179], v[192:195], v[50:53]
	v_mfma_f32_16x16x32_bf16 v[46:49], v[150:153], v[200:203], v[46:49]
	v_mfma_f32_16x16x32_bf16 v[42:45], v[176:179], v[200:203], v[42:45]
	v_mfma_f32_16x16x32_bf16 v[38:41], v[150:153], v[224:227], v[38:41]
	v_mfma_f32_16x16x32_bf16 v[34:37], v[176:179], v[224:227], v[34:37]
	s_setprio 0
	s_barrier
; #define PG8_STAGE(bufoff, gbase, voff) do { _Pragma("unroll") for (int _i = 0; _i < 2; ++_i) \
;         __builtin_amdgcn_global_load_lds((const unsigned*)((const char*)(gbase) + (voff)[_i]), (PG8_LAS unsigned*)(lds + (bufoff) + ldsw + _i * 8192), 16, 0, 0); } while (0)
; #define PG8_LDA(dst, b, h) do { _Pragma("unroll") for (int m = 0; m < 4; ++m) _Pragma("unroll") for (int k = 0; k < 2; ++k) dst[m][k] = *(const PG8_LAS bf16x8*)(lds + PG8_SA(b, h) + aoff + m * 2048 + k * 1024); } while (0)
; #define PG8_MMA(ai, bj, At, Bt) do { __builtin_amdgcn_s_setprio(1); _Pragma("unroll") for (int m = 0; m < 4; ++m) _Pragma("unroll") for (int n = 0; n < 2; ++n) _Pragma("unroll") for (int k = 0; k < 2; ++k) \
;         acc[ai][bj][m][n] = __builtin_amdgcn_mfma_f32_16x16x32_bf16(Bt[n][k], At[m][k], acc[ai][bj][m][n], 0, 0, 0); __builtin_amdgcn_s_setprio(0); } while (0)
; #define PG8_WAIT_V(n) asm volatile("s_waitcnt vmcnt(" #n ")" ::: "memory")
; #define PG8_WAIT_L(n) asm volatile("s_waitcnt lgkmcnt(" #n ")" ::: "memory")
; #define PG8_BAR __builtin_amdgcn_s_barrier()
; #define PG8_SCHED __builtin_amdgcn_sched_barrier(0)
; template <class Epi, class Sched>
; __device__ __forceinline__ void gemm_phase(PG8_LAS unsigned char* lds, const Gemm g, const Sched& S, const Epi& E) {
;     ...
;             PG8_LDA(At, 1, 1); PG8_STAGE(PG8_SB(1, 0), b3, voffB); PG8_STAGE(PG8_SB(1, 1), b3 + hstepB, voffB); PG8_STAGE(PG8_SA(1, 0), a3, voffA);
;             PG8_WAIT_V(8); PG8_WAIT_L(0); PG8_BAR; PG8_MMA(1, 0, At, B0); PG8_MMA(1, 1, At, B1); PG8_BAR; PG8_SCHED;
;         }
;         if (wr == 0) PG8_BAR;
	s_add_i32 s9, s9, s81
	v_lshl_add_u64 v[168:169], v[168:169], 0, s[22:23]
	s_mov_b32 m0, s9
	ds_read_b128 v[180:183], v218 offset:49152
	ds_read_b128 v[184:187], v218 offset:50176
	ds_read_b128 v[188:191], v218 offset:51200
	ds_read_b128 v[192:195], v218 offset:52224
	ds_read_b128 v[196:199], v218 offset:53248
	ds_read_b128 v[200:203], v218 offset:54272
	ds_read_b128 v[220:223], v218 offset:55296
	ds_read_b128 v[224:227], v218 offset:56320
	global_load_lds_dwordx4 v[168:169], off
	s_add_i32 m0, s9, 0x2000
	s_add_u32 s64, s64, 0x40080
	v_lshl_add_u64 v[168:169], v[204:205], 0, s[22:23]
	s_addc_u32 s65, s65, 0
	s_add_i32 s9, s10, s81
	global_load_lds_dwordx4 v[168:169], off
	v_lshl_add_u64 v[168:169], s[64:65], 0, v[0:1]
	s_mov_b32 m0, s9
	s_nop 0
	global_load_lds_dwordx4 v[168:169], off
	v_lshl_add_u64 v[168:169], s[64:65], 0, v[170:171]
	s_add_i32 m0, s9, 0x2000
	s_nop 0
	global_load_lds_dwordx4 v[168:169], off
	v_lshl_add_u64 v[168:169], v[228:229], 0, s[22:23]
	s_mov_b32 m0, s20
	s_nop 0
	global_load_lds_dwordx4 v[168:169], off
	v_lshl_add_u64 v[168:169], v[230:231], 0, s[22:23]
	s_mov_b32 m0, s85
	s_nop 0
	global_load_lds_dwordx4 v[168:169], off
	s_waitcnt vmcnt(8)
	s_waitcnt lgkmcnt(0)
	s_barrier
	s_setprio 1
	s_waitcnt lgkmcnt(0)
	v_mfma_f32_16x16x32_bf16 v[94:97], v[130:133], v[180:183], v[94:97]
	v_mfma_f32_16x16x32_bf16 v[90:93], v[138:141], v[180:183], v[90:93]
	v_mfma_f32_16x16x32_bf16 v[86:89], v[130:133], v[188:191], v[86:89]
	v_mfma_f32_16x16x32_bf16 v[82:85], v[138:141], v[188:191], v[82:85]
	v_mfma_f32_16x16x32_bf16 v[78:81], v[130:133], v[196:199], v[78:81]
	v_mfma_f32_16x16x32_bf16 v[74:77], v[138:141], v[196:199], v[74:77]
	v_mfma_f32_16x16x32_bf16 v[70:73], v[130:133], v[220:223], v[70:73]
	v_mfma_f32_16x16x32_bf16 v[66:69], v[138:141], v[220:223], v[66:69]
	v_mfma_f32_16x16x32_bf16 v[94:97], v[134:137], v[184:187], v[94:97]
	v_mfma_f32_16x16x32_bf16 v[90:93], v[142:145], v[184:187], v[90:93]
	v_mfma_f32_16x16x32_bf16 v[86:89], v[134:137], v[192:195], v[86:89]
	v_mfma_f32_16x16x32_bf16 v[82:85], v[142:145], v[192:195], v[82:85]
	v_mfma_f32_16x16x32_bf16 v[78:81], v[134:137], v[200:203], v[78:81]
	v_mfma_f32_16x16x32_bf16 v[74:77], v[142:145], v[200:203], v[74:77]
	v_mfma_f32_16x16x32_bf16 v[70:73], v[134:137], v[224:227], v[70:73]
	v_mfma_f32_16x16x32_bf16 v[66:69], v[142:145], v[224:227], v[66:69]
	v_mfma_f32_16x16x32_bf16 v[30:33], v[146:149], v[180:183], v[30:33]
	v_mfma_f32_16x16x32_bf16 v[26:29], v[154:157], v[180:183], v[26:29]
	v_mfma_f32_16x16x32_bf16 v[22:25], v[146:149], v[188:191], v[22:25]
	v_mfma_f32_16x16x32_bf16 v[18:21], v[154:157], v[188:191], v[18:21]
	v_mfma_f32_16x16x32_bf16 v[14:17], v[146:149], v[196:199], v[14:17]
	v_mfma_f32_16x16x32_bf16 v[10:13], v[154:157], v[196:199], v[10:13]
	v_mfma_f32_16x16x32_bf16 v[6:9], v[146:149], v[220:223], v[6:9]
	v_mfma_f32_16x16x32_bf16 v[2:5], v[154:157], v[220:223], v[2:5]
	v_mfma_f32_16x16x32_bf16 v[30:33], v[150:153], v[184:187], v[30:33]
	v_mfma_f32_16x16x32_bf16 v[26:29], v[176:179], v[184:187], v[26:29]
	v_mfma_f32_16x16x32_bf16 v[22:25], v[150:153], v[192:195], v[22:25]
	v_mfma_f32_16x16x32_bf16 v[18:21], v[176:179], v[192:195], v[18:21]
	v_mfma_f32_16x16x32_bf16 v[14:17], v[150:153], v[200:203], v[14:17]
	v_mfma_f32_16x16x32_bf16 v[10:13], v[176:179], v[200:203], v[10:13]
	v_mfma_f32_16x16x32_bf16 v[6:9], v[150:153], v[224:227], v[6:9]
	v_mfma_f32_16x16x32_bf16 v[2:5], v[176:179], v[224:227], v[2:5]
	s_setprio 0
	s_barrier
	s_add_i32 s8, s8, 2
	s_add_u32 s28, s28, 0x100
	s_addc_u32 s29, s29, 0
	s_add_u32 s7, s7, 0x100
	s_addc_u32 s88, s88, 0
	s_cmp_gt_u32 s8, 13
	s_cbranch_scc0 .LBB0_197
	s_and_b64 vcc, exec, s[38:39]
	s_cbranch_vccz .LBB0_200
	s_barrier

; #define PG8_STAGE(bufoff, gbase, voff) do { _Pragma("unroll") for (int _i = 0; _i < 2; ++_i) \
;         __builtin_amdgcn_global_load_lds((const unsigned*)((const char*)(gbase) + (voff)[_i]), (PG8_LAS unsigned*)(lds + (bufoff) + ldsw + _i * 8192), 16, 0, 0); } while (0)
; #define PG8_LDA(dst, b, h) do { _Pragma("unroll") for (int m = 0; m < 4; ++m) _Pragma("unroll") for (int k = 0; k < 2; ++k) dst[m][k] = *(const PG8_LAS bf16x8*)(lds + PG8_SA(b, h) + aoff + m * 2048 + k * 1024); } while (0)
; #define PG8_LDB(dst, b, h) do { _Pragma("unroll") for (int n = 0; n < 2; ++n) _Pragma("unroll") for (int k = 0; k < 2; ++k) dst[n][k] = *(const PG8_LAS bf16x8*)(lds + PG8_SB(b, h) + boff + n * 2048 + k * 1024); } while (0)
; #define PG8_MMA(ai, bj, At, Bt) do { __builtin_amdgcn_s_setprio(1); _Pragma("unroll") for (int m = 0; m < 4; ++m) _Pragma("unroll") for (int n = 0; n < 2; ++n) _Pragma("unroll") for (int k = 0; k < 2; ++k) \
;         acc[ai][bj][m][n] = __builtin_amdgcn_mfma_f32_16x16x32_bf16(Bt[n][k], At[m][k], acc[ai][bj][m][n], 0, 0, 0); __builtin_amdgcn_s_setprio(0); } while (0)
; #define PG8_WAIT_V(n) asm volatile("s_waitcnt vmcnt(" #n ")" ::: "memory")
; #define PG8_WAIT_L(n) asm volatile("s_waitcnt lgkmcnt(" #n ")" ::: "memory")
; #define PG8_BAR __builtin_amdgcn_s_barrier()
; #define PG8_SCHED __builtin_amdgcn_sched_barrier(0)
; template <class Epi, class Sched>
; __device__ __forceinline__ void gemm_phase(PG8_LAS unsigned char* lds, const Gemm g, const Sched& S, const Epi& E) {
;     ...
;         for (int t = 0; t < nt; t += 2) {
;             const bool last = (t == nt - 2);
;             const char* a1 = cA + (size_t)(t + 1) * kstep;
;             const char* a2 = last ? nA : cA + (size_t)(t + 2) * kstep; const char* b2 = last ? nB : cB + (size_t)(t + 2) * kstep;
;             const char* a3 = a2 + kstep; const char* b3 = b2 + kstep;
;             PG8_LDB(B0, 0, 0); PG8_LDB(B1, 0, 1); PG8_SCHED; PG8_LDA(At, 0, 0); PG8_STAGE(PG8_SA(1, 1), a1 + hstepA, voffA);
;             PG8_WAIT_V(8); PG8_WAIT_L(0); PG8_BAR; PG8_MMA(0, 0, At, B0); PG8_MMA(0, 1, At, B1); PG8_BAR; PG8_SCHED;
;             PG8_LDA(At, 0, 1); PG8_STAGE(PG8_SB(0, 0), b2, voffB); PG8_STAGE(PG8_SB(0, 1), b2 + hstepB, voffB); PG8_STAGE(PG8_SA(0, 0), a2, voffA);
;             PG8_WAIT_V(8); PG8_WAIT_L(0); PG8_BAR; PG8_MMA(1, 0, At, B0); PG8_MMA(1, 1, At, B1); PG8_BAR; PG8_SCHED;
.LBB0_277:
	s_add_u32 s9, s28, 0xfff80080
	s_addc_u32 s10, s29, -1
	s_add_i32 s11, 0, 0x10000
	s_cmp_eq_u32 s8, 28
	s_cselect_b32 vcc_hi, s4, s10
	s_cselect_b32 vcc_lo, s5, s9
	v_add_u32_e32 v0, s11, v182
	s_cselect_b32 s45, s13, s15
	s_cselect_b32 s44, s6, s7
	s_add_i32 s9, 0, 0x14000
	ds_read_b128 v[130:133], v0
	ds_read_b128 v[148:151], v0 offset:1024
	ds_read_b128 v[152:155], v0 offset:2048
	ds_read_b128 v[156:159], v0 offset:3072
	v_add_u32_e32 v0, s9, v182
	ds_read_b128 v[170:173], v0
	ds_read_b128 v[174:177], v0 offset:1024
	ds_read_b128 v[178:181], v0 offset:2048
	ds_read_b128 v[202:205], v0 offset:3072
	v_lshl_add_u64 v[160:161], s[28:29], 0, v[144:145]
	s_add_i32 m0, s39, 0xc000
	ds_read_b128 v[216:219], v200
	ds_read_b128 v[220:223], v200 offset:1024
	ds_read_b128 v[224:227], v200 offset:2048
	ds_read_b128 v[228:231], v200 offset:3072
	ds_read_b128 v[232:235], v200 offset:4096
	ds_read_b128 v[236:239], v200 offset:5120
	ds_read_b128 v[240:243], v200 offset:6144
	ds_read_b128 v[244:247], v200 offset:7168
	global_load_lds_dwordx4 v[160:161], off
	v_lshl_add_u64 v[160:161], s[28:29], 0, v[146:147]
	s_add_i32 m0, s39, 0xe000
	s_nop 0
	global_load_lds_dwordx4 v[160:161], off
	s_waitcnt vmcnt(8)
	s_waitcnt lgkmcnt(0)
	s_barrier
	s_setprio 1
	s_waitcnt lgkmcnt(0)
	v_mfma_f32_16x16x32_bf16 v[126:129], v[130:133], v[216:219], v[126:129]
	v_mfma_f32_16x16x32_bf16 v[122:125], v[152:155], v[216:219], v[122:125]
	v_mfma_f32_16x16x32_bf16 v[110:113], v[130:133], v[224:227], v[110:113]
	v_mfma_f32_16x16x32_bf16 v[106:109], v[152:155], v[224:227], v[106:109]
	v_mfma_f32_16x16x32_bf16 v[94:97], v[130:133], v[232:235], v[94:97]
	v_mfma_f32_16x16x32_bf16 v[90:93], v[152:155], v[232:235], v[90:93]
	v_mfma_f32_16x16x32_bf16 v[78:81], v[130:133], v[240:243], v[78:81]
	v_mfma_f32_16x16x32_bf16 v[74:77], v[152:155], v[240:243], v[74:77]
	v_mfma_f32_16x16x32_bf16 v[126:129], v[148:151], v[220:223], v[126:129]
	v_mfma_f32_16x16x32_bf16 v[122:125], v[156:159], v[220:223], v[122:125]
	v_mfma_f32_16x16x32_bf16 v[110:113], v[148:151], v[228:231], v[110:113]
	v_mfma_f32_16x16x32_bf16 v[106:109], v[156:159], v[228:231], v[106:109]
	v_mfma_f32_16x16x32_bf16 v[94:97], v[148:151], v[236:239], v[94:97]
	v_mfma_f32_16x16x32_bf16 v[90:93], v[156:159], v[236:239], v[90:93]
	v_mfma_f32_16x16x32_bf16 v[78:81], v[148:151], v[244:247], v[78:81]
	v_mfma_f32_16x16x32_bf16 v[74:77], v[156:159], v[244:247], v[74:77]
	v_mfma_f32_16x16x32_bf16 v[118:121], v[170:173], v[216:219], v[118:121]
	v_mfma_f32_16x16x32_bf16 v[114:117], v[178:181], v[216:219], v[114:117]
	v_mfma_f32_16x16x32_bf16 v[102:105], v[170:173], v[224:227], v[102:105]
	v_mfma_f32_16x16x32_bf16 v[98:101], v[178:181], v[224:227], v[98:101]
	v_mfma_f32_16x16x32_bf16 v[86:89], v[170:173], v[232:235], v[86:89]
	v_mfma_f32_16x16x32_bf16 v[82:85], v[178:181], v[232:235], v[82:85]
	v_mfma_f32_16x16x32_bf16 v[70:73], v[170:173], v[240:243], v[70:73]
	v_mfma_f32_16x16x32_bf16 v[66:69], v[178:181], v[240:243], v[66:69]
	v_mfma_f32_16x16x32_bf16 v[118:121], v[174:177], v[220:223], v[118:121]
	v_mfma_f32_16x16x32_bf16 v[114:117], v[202:205], v[220:223], v[114:117]
	v_mfma_f32_16x16x32_bf16 v[102:105], v[174:177], v[228:231], v[102:105]
	v_mfma_f32_16x16x32_bf16 v[98:101], v[202:205], v[228:231], v[98:101]
	v_mfma_f32_16x16x32_bf16 v[86:89], v[174:177], v[236:239], v[86:89]
	v_mfma_f32_16x16x32_bf16 v[82:85], v[202:205], v[236:239], v[82:85]
	v_mfma_f32_16x16x32_bf16 v[70:73], v[174:177], v[244:247], v[70:73]
	v_mfma_f32_16x16x32_bf16 v[66:69], v[202:205], v[244:247], v[66:69]
	s_setprio 0
	s_barrier
	s_add_i32 s10, s11, s20
	v_lshl_add_u64 v[160:161], s[44:45], 0, v[136:137]
	s_mov_b32 m0, s10
	ds_read_b128 v[216:219], v200 offset:16384
	ds_read_b128 v[220:223], v200 offset:17408
	ds_read_b128 v[224:227], v200 offset:18432
	ds_read_b128 v[228:231], v200 offset:19456
	ds_read_b128 v[232:235], v200 offset:20480
	ds_read_b128 v[236:239], v200 offset:21504
	ds_read_b128 v[240:243], v200 offset:22528
	ds_read_b128 v[244:247], v200 offset:23552
	global_load_lds_dwordx4 v[160:161], off
	s_add_i32 m0, s10, 0x2000
	s_add_u32 s90, s44, 0x80000
	v_lshl_add_u64 v[248:249], s[44:45], 0, v[140:141]
	s_addc_u32 s91, s45, 0
	s_add_i32 s9, s9, s20
	global_load_lds_dwordx4 v[248:249], off
	v_lshl_add_u64 v[250:251], s[90:91], 0, v[136:137]
	s_mov_b32 m0, s9
	v_lshl_add_u64 v[252:253], vcc, 0, v[138:139]
	global_load_lds_dwordx4 v[250:251], off
	v_lshl_add_u64 v[250:251], s[90:91], 0, v[140:141]
	s_add_i32 m0, s9, 0x2000
	s_nop 0
	global_load_lds_dwordx4 v[250:251], off
	v_lshl_add_u64 v[250:251], vcc, 0, v[134:135]
	s_mov_b32 m0, s39
	s_nop 0
	global_load_lds_dwordx4 v[250:251], off
	s_mov_b32 m0, s69
	s_nop 0
	global_load_lds_dwordx4 v[252:253], off
	s_waitcnt vmcnt(8)
	s_waitcnt lgkmcnt(0)
	s_barrier
; #define PG8_STAGE(bufoff, gbase, voff) do { _Pragma("unroll") for (int _i = 0; _i < 2; ++_i) \
;         __builtin_amdgcn_global_load_lds((const unsigned*)((const char*)(gbase) + (voff)[_i]), (PG8_LAS unsigned*)(lds + (bufoff) + ldsw + _i * 8192), 16, 0, 0); } while (0)
; #define PG8_LDA(dst, b, h) do { _Pragma("unroll") for (int m = 0; m < 4; ++m) _Pragma("unroll") for (int k = 0; k < 2; ++k) dst[m][k] = *(const PG8_LAS bf16x8*)(lds + PG8_SA(b, h) + aoff + m * 2048 + k * 1024); } while (0)
; #define PG8_LDB(dst, b, h) do { _Pragma("unroll") for (int n = 0; n < 2; ++n) _Pragma("unroll") for (int k = 0; k < 2; ++k) dst[n][k] = *(const PG8_LAS bf16x8*)(lds + PG8_SB(b, h) + boff + n * 2048 + k * 1024); } while (0)
; #define PG8_MMA(ai, bj, At, Bt) do { __builtin_amdgcn_s_setprio(1); _Pragma("unroll") for (int m = 0; m < 4; ++m) _Pragma("unroll") for (int n = 0; n < 2; ++n) _Pragma("unroll") for (int k = 0; k < 2; ++k) \
;         acc[ai][bj][m][n] = __builtin_amdgcn_mfma_f32_16x16x32_bf16(Bt[n][k], At[m][k], acc[ai][bj][m][n], 0, 0, 0); __builtin_amdgcn_s_setprio(0); } while (0)
; #define PG8_WAIT_V(n) asm volatile("s_waitcnt vmcnt(" #n ")" ::: "memory")
; #define PG8_WAIT_L(n) asm volatile("s_waitcnt lgkmcnt(" #n ")" ::: "memory")
; #define PG8_BAR __builtin_amdgcn_s_barrier()
; #define PG8_SCHED __builtin_amdgcn_sched_barrier(0)
; template <class Epi, class Sched>
; __device__ __forceinline__ void gemm_phase(PG8_LAS unsigned char* lds, const Gemm g, const Sched& S, const Epi& E) {
;     ...
;             PG8_WAIT_V(8); PG8_WAIT_L(0); PG8_BAR; PG8_MMA(1, 0, At, B0); PG8_MMA(1, 1, At, B1); PG8_BAR; PG8_SCHED;
;             PG8_LDB(B0, 1, 0); PG8_LDB(B1, 1, 1); PG8_SCHED; PG8_LDA(At, 1, 0); PG8_STAGE(PG8_SA(0, 1), a2 + hstepA, voffA);
;             PG8_WAIT_V(8); PG8_WAIT_L(0); PG8_BAR; PG8_MMA(0, 0, At, B0); PG8_MMA(0, 1, At, B1); PG8_BAR; PG8_SCHED;
	s_setprio 1
	s_waitcnt lgkmcnt(0)
	v_mfma_f32_16x16x32_bf16 v[62:65], v[130:133], v[216:219], v[62:65]
	v_mfma_f32_16x16x32_bf16 v[58:61], v[152:155], v[216:219], v[58:61]
	v_mfma_f32_16x16x32_bf16 v[46:49], v[130:133], v[224:227], v[46:49]
	v_mfma_f32_16x16x32_bf16 v[42:45], v[152:155], v[224:227], v[42:45]
	v_mfma_f32_16x16x32_bf16 v[30:33], v[130:133], v[232:235], v[30:33]
	v_mfma_f32_16x16x32_bf16 v[26:29], v[152:155], v[232:235], v[26:29]
	v_mfma_f32_16x16x32_bf16 v[14:17], v[130:133], v[240:243], v[14:17]
	v_mfma_f32_16x16x32_bf16 v[10:13], v[152:155], v[240:243], v[10:13]
	v_mfma_f32_16x16x32_bf16 v[62:65], v[148:151], v[220:223], v[62:65]
	v_mfma_f32_16x16x32_bf16 v[58:61], v[156:159], v[220:223], v[58:61]
	v_mfma_f32_16x16x32_bf16 v[46:49], v[148:151], v[228:231], v[46:49]
	v_mfma_f32_16x16x32_bf16 v[42:45], v[156:159], v[228:231], v[42:45]
	v_mfma_f32_16x16x32_bf16 v[30:33], v[148:151], v[236:239], v[30:33]
	v_mfma_f32_16x16x32_bf16 v[26:29], v[156:159], v[236:239], v[26:29]
	v_mfma_f32_16x16x32_bf16 v[14:17], v[148:151], v[244:247], v[14:17]
	v_mfma_f32_16x16x32_bf16 v[10:13], v[156:159], v[244:247], v[10:13]
	v_mfma_f32_16x16x32_bf16 v[54:57], v[170:173], v[216:219], v[54:57]
	v_mfma_f32_16x16x32_bf16 v[50:53], v[178:181], v[216:219], v[50:53]
	v_mfma_f32_16x16x32_bf16 v[38:41], v[170:173], v[224:227], v[38:41]
	v_mfma_f32_16x16x32_bf16 v[34:37], v[178:181], v[224:227], v[34:37]
	v_mfma_f32_16x16x32_bf16 v[22:25], v[170:173], v[232:235], v[22:25]
	v_mfma_f32_16x16x32_bf16 v[18:21], v[178:181], v[232:235], v[18:21]
	v_mfma_f32_16x16x32_bf16 v[6:9], v[170:173], v[240:243], v[6:9]
	v_mfma_f32_16x16x32_bf16 v[2:5], v[178:181], v[240:243], v[2:5]
	v_mfma_f32_16x16x32_bf16 v[54:57], v[174:177], v[220:223], v[54:57]
	v_mfma_f32_16x16x32_bf16 v[50:53], v[202:205], v[220:223], v[50:53]
	v_mfma_f32_16x16x32_bf16 v[38:41], v[174:177], v[228:231], v[38:41]
	v_mfma_f32_16x16x32_bf16 v[34:37], v[202:205], v[228:231], v[34:37]
	v_mfma_f32_16x16x32_bf16 v[22:25], v[174:177], v[236:239], v[22:25]
	v_mfma_f32_16x16x32_bf16 v[18:21], v[202:205], v[236:239], v[18:21]
	v_mfma_f32_16x16x32_bf16 v[6:9], v[174:177], v[244:247], v[6:9]
	v_mfma_f32_16x16x32_bf16 v[2:5], v[202:205], v[244:247], v[2:5]
	s_setprio 0
	s_barrier
	s_add_i32 s9, 0, 0x18000
	v_add_u32_e32 v0, s9, v182
	s_add_i32 s10, 0, 0x1c000
	ds_read_b128 v[130:133], v0
	ds_read_b128 v[148:151], v0 offset:1024
	ds_read_b128 v[152:155], v0 offset:2048
	ds_read_b128 v[156:159], v0 offset:3072
	v_add_u32_e32 v0, s10, v182
	ds_read_b128 v[170:173], v0
	ds_read_b128 v[174:177], v0 offset:1024
	ds_read_b128 v[178:181], v0 offset:2048
	ds_read_b128 v[202:205], v0 offset:3072
	s_add_u32 s90, vcc_lo, 0x80000
	s_addc_u32 s91, vcc_hi, 0
	s_mov_b32 m0, s80
	v_lshl_add_u64 v[168:169], s[90:91], 0, v[134:135]
	ds_read_b128 v[216:219], v200 offset:32768
	ds_read_b128 v[220:223], v200 offset:33792
	ds_read_b128 v[224:227], v200 offset:34816
	ds_read_b128 v[228:231], v200 offset:35840
	ds_read_b128 v[232:235], v200 offset:36864
	ds_read_b128 v[236:239], v200 offset:37888
	ds_read_b128 v[240:243], v200 offset:38912
	ds_read_b128 v[244:247], v200 offset:39936
	global_load_lds_dwordx4 v[168:169], off
	v_lshl_add_u64 v[168:169], s[90:91], 0, v[138:139]
	s_mov_b32 m0, s81
	s_nop 0
	global_load_lds_dwordx4 v[168:169], off
	s_waitcnt vmcnt(8)
	s_waitcnt lgkmcnt(0)
	s_barrier
	s_setprio 1
	s_waitcnt lgkmcnt(0)
	v_mfma_f32_16x16x32_bf16 v[126:129], v[130:133], v[216:219], v[126:129]
	v_mfma_f32_16x16x32_bf16 v[122:125], v[152:155], v[216:219], v[122:125]
	v_mfma_f32_16x16x32_bf16 v[110:113], v[130:133], v[224:227], v[110:113]
	v_mfma_f32_16x16x32_bf16 v[106:109], v[152:155], v[224:227], v[106:109]
	v_mfma_f32_16x16x32_bf16 v[94:97], v[130:133], v[232:235], v[94:97]
	v_mfma_f32_16x16x32_bf16 v[90:93], v[152:155], v[232:235], v[90:93]
	v_mfma_f32_16x16x32_bf16 v[78:81], v[130:133], v[240:243], v[78:81]
	v_mfma_f32_16x16x32_bf16 v[74:77], v[152:155], v[240:243], v[74:77]
	v_mfma_f32_16x16x32_bf16 v[126:129], v[148:151], v[220:223], v[126:129]
	v_mfma_f32_16x16x32_bf16 v[122:125], v[156:159], v[220:223], v[122:125]
	v_mfma_f32_16x16x32_bf16 v[110:113], v[148:151], v[228:231], v[110:113]
	v_mfma_f32_16x16x32_bf16 v[106:109], v[156:159], v[228:231], v[106:109]
	v_mfma_f32_16x16x32_bf16 v[94:97], v[148:151], v[236:239], v[94:97]
	v_mfma_f32_16x16x32_bf16 v[90:93], v[156:159], v[236:239], v[90:93]
	v_mfma_f32_16x16x32_bf16 v[78:81], v[148:151], v[244:247], v[78:81]
	v_mfma_f32_16x16x32_bf16 v[74:77], v[156:159], v[244:247], v[74:77]
	v_mfma_f32_16x16x32_bf16 v[118:121], v[170:173], v[216:219], v[118:121]
	v_mfma_f32_16x16x32_bf16 v[114:117], v[178:181], v[216:219], v[114:117]
	v_mfma_f32_16x16x32_bf16 v[102:105], v[170:173], v[224:227], v[102:105]
	v_mfma_f32_16x16x32_bf16 v[98:101], v[178:181], v[224:227], v[98:101]
	v_mfma_f32_16x16x32_bf16 v[86:89], v[170:173], v[232:235], v[86:89]
	v_mfma_f32_16x16x32_bf16 v[82:85], v[178:181], v[232:235], v[82:85]
	v_mfma_f32_16x16x32_bf16 v[70:73], v[170:173], v[240:243], v[70:73]
	v_mfma_f32_16x16x32_bf16 v[66:69], v[178:181], v[240:243], v[66:69]
	v_mfma_f32_16x16x32_bf16 v[118:121], v[174:177], v[220:223], v[118:121]
	v_mfma_f32_16x16x32_bf16 v[114:117], v[202:205], v[220:223], v[114:117]
	v_mfma_f32_16x16x32_bf16 v[102:105], v[174:177], v[228:231], v[102:105]
	v_mfma_f32_16x16x32_bf16 v[98:101], v[202:205], v[228:231], v[98:101]
	v_mfma_f32_16x16x32_bf16 v[86:89], v[174:177], v[236:239], v[86:89]
	v_mfma_f32_16x16x32_bf16 v[82:85], v[202:205], v[236:239], v[82:85]
	v_mfma_f32_16x16x32_bf16 v[70:73], v[174:177], v[244:247], v[70:73]
	v_mfma_f32_16x16x32_bf16 v[66:69], v[202:205], v[244:247], v[66:69]
	s_setprio 0
	s_barrier
; #define PG8_STAGE(bufoff, gbase, voff) do { _Pragma("unroll") for (int _i = 0; _i < 2; ++_i) \
;         __builtin_amdgcn_global_load_lds((const unsigned*)((const char*)(gbase) + (voff)[_i]), (PG8_LAS unsigned*)(lds + (bufoff) + ldsw + _i * 8192), 16, 0, 0); } while (0)
; #define PG8_LDA(dst, b, h) do { _Pragma("unroll") for (int m = 0; m < 4; ++m) _Pragma("unroll") for (int k = 0; k < 2; ++k) dst[m][k] = *(const PG8_LAS bf16x8*)(lds + PG8_SA(b, h) + aoff + m * 2048 + k * 1024); } while (0)
; #define PG8_MMA(ai, bj, At, Bt) do { __builtin_amdgcn_s_setprio(1); _Pragma("unroll") for (int m = 0; m < 4; ++m) _Pragma("unroll") for (int n = 0; n < 2; ++n) _Pragma("unroll") for (int k = 0; k < 2; ++k) \
;         acc[ai][bj][m][n] = __builtin_amdgcn_mfma_f32_16x16x32_bf16(Bt[n][k], At[m][k], acc[ai][bj][m][n], 0, 0, 0); __builtin_amdgcn_s_setprio(0); } while (0)
; #define PG8_WAIT_V(n) asm volatile("s_waitcnt vmcnt(" #n ")" ::: "memory")
; #define PG8_WAIT_L(n) asm volatile("s_waitcnt lgkmcnt(" #n ")" ::: "memory")
; #define PG8_BAR __builtin_amdgcn_s_barrier()
; #define PG8_SCHED __builtin_amdgcn_sched_barrier(0)
; template <class Epi, class Sched>
; __device__ __forceinline__ void gemm_phase(PG8_LAS unsigned char* lds, const Gemm g, const Sched& S, const Epi& E) {
;     ...
;             PG8_LDA(At, 1, 1); PG8_STAGE(PG8_SB(1, 0), b3, voffB); PG8_STAGE(PG8_SB(1, 1), b3 + hstepB, voffB); PG8_STAGE(PG8_SA(1, 0), a3, voffA);
;             PG8_WAIT_V(8); PG8_WAIT_L(0); PG8_BAR; PG8_MMA(1, 0, At, B0); PG8_MMA(1, 1, At, B1); PG8_BAR; PG8_SCHED;
;         }
;         if (wr == 0) PG8_BAR;
	s_add_i32 s9, s9, s20
	v_lshl_add_u64 v[160:161], v[160:161], 0, s[22:23]
	s_mov_b32 m0, s9
	ds_read_b128 v[216:219], v200 offset:49152
	ds_read_b128 v[220:223], v200 offset:50176
	ds_read_b128 v[224:227], v200 offset:51200
	ds_read_b128 v[228:231], v200 offset:52224
	ds_read_b128 v[232:235], v200 offset:53248
	ds_read_b128 v[236:239], v200 offset:54272
	ds_read_b128 v[240:243], v200 offset:55296
	ds_read_b128 v[244:247], v200 offset:56320
	global_load_lds_dwordx4 v[160:161], off
	s_add_i32 m0, s9, 0x2000
	s_add_u32 s44, s44, 0x80080
	v_lshl_add_u64 v[160:161], v[248:249], 0, s[22:23]
	s_addc_u32 s45, s45, 0
	s_add_i32 s9, s10, s20
	global_load_lds_dwordx4 v[160:161], off
	v_lshl_add_u64 v[160:161], s[44:45], 0, v[136:137]
	s_mov_b32 m0, s9
	s_nop 0
	global_load_lds_dwordx4 v[160:161], off
	v_lshl_add_u64 v[160:161], s[44:45], 0, v[140:141]
	s_add_i32 m0, s9, 0x2000
	s_nop 0
	global_load_lds_dwordx4 v[160:161], off
	v_lshl_add_u64 v[160:161], v[250:251], 0, s[22:23]
	s_mov_b32 m0, s82
	s_nop 0
	global_load_lds_dwordx4 v[160:161], off
	v_lshl_add_u64 v[160:161], v[252:253], 0, s[22:23]
	s_mov_b32 m0, s83
	s_nop 0
	global_load_lds_dwordx4 v[160:161], off
	s_waitcnt vmcnt(8)
	s_waitcnt lgkmcnt(0)
	s_barrier
	s_setprio 1
	s_waitcnt lgkmcnt(0)
	v_mfma_f32_16x16x32_bf16 v[62:65], v[130:133], v[216:219], v[62:65]
	v_mfma_f32_16x16x32_bf16 v[58:61], v[152:155], v[216:219], v[58:61]
	v_mfma_f32_16x16x32_bf16 v[46:49], v[130:133], v[224:227], v[46:49]
	v_mfma_f32_16x16x32_bf16 v[42:45], v[152:155], v[224:227], v[42:45]
	v_mfma_f32_16x16x32_bf16 v[30:33], v[130:133], v[232:235], v[30:33]
	v_mfma_f32_16x16x32_bf16 v[26:29], v[152:155], v[232:235], v[26:29]
	v_mfma_f32_16x16x32_bf16 v[14:17], v[130:133], v[240:243], v[14:17]
	v_mfma_f32_16x16x32_bf16 v[10:13], v[152:155], v[240:243], v[10:13]
	v_mfma_f32_16x16x32_bf16 v[62:65], v[148:151], v[220:223], v[62:65]
	v_mfma_f32_16x16x32_bf16 v[58:61], v[156:159], v[220:223], v[58:61]
	v_mfma_f32_16x16x32_bf16 v[46:49], v[148:151], v[228:231], v[46:49]
	v_mfma_f32_16x16x32_bf16 v[42:45], v[156:159], v[228:231], v[42:45]
	v_mfma_f32_16x16x32_bf16 v[30:33], v[148:151], v[236:239], v[30:33]
	v_mfma_f32_16x16x32_bf16 v[26:29], v[156:159], v[236:239], v[26:29]
	v_mfma_f32_16x16x32_bf16 v[14:17], v[148:151], v[244:247], v[14:17]
	v_mfma_f32_16x16x32_bf16 v[10:13], v[156:159], v[244:247], v[10:13]
	v_mfma_f32_16x16x32_bf16 v[54:57], v[170:173], v[216:219], v[54:57]
	v_mfma_f32_16x16x32_bf16 v[50:53], v[178:181], v[216:219], v[50:53]
	v_mfma_f32_16x16x32_bf16 v[38:41], v[170:173], v[224:227], v[38:41]
	v_mfma_f32_16x16x32_bf16 v[34:37], v[178:181], v[224:227], v[34:37]
	v_mfma_f32_16x16x32_bf16 v[22:25], v[170:173], v[232:235], v[22:25]
	v_mfma_f32_16x16x32_bf16 v[18:21], v[178:181], v[232:235], v[18:21]
	v_mfma_f32_16x16x32_bf16 v[6:9], v[170:173], v[240:243], v[6:9]
	v_mfma_f32_16x16x32_bf16 v[2:5], v[178:181], v[240:243], v[2:5]
	v_mfma_f32_16x16x32_bf16 v[54:57], v[174:177], v[220:223], v[54:57]
	v_mfma_f32_16x16x32_bf16 v[50:53], v[202:205], v[220:223], v[50:53]
	v_mfma_f32_16x16x32_bf16 v[38:41], v[174:177], v[228:231], v[38:41]
	v_mfma_f32_16x16x32_bf16 v[34:37], v[202:205], v[228:231], v[34:37]
	v_mfma_f32_16x16x32_bf16 v[22:25], v[174:177], v[236:239], v[22:25]
	v_mfma_f32_16x16x32_bf16 v[18:21], v[202:205], v[236:239], v[18:21]
	v_mfma_f32_16x16x32_bf16 v[6:9], v[174:177], v[244:247], v[6:9]
	v_mfma_f32_16x16x32_bf16 v[2:5], v[202:205], v[244:247], v[2:5]
	s_setprio 0
	s_barrier
	s_add_i32 s8, s8, 2
	s_add_u32 s28, s28, 0x100
	s_addc_u32 s29, s29, 0
	s_add_u32 s7, s7, 0x100
	s_addc_u32 s15, s15, 0
	s_cmp_gt_u32 s8, 29
	s_cbranch_scc0 .LBB0_277
	s_and_b64 vcc, exec, s[60:61]
	s_cbranch_vccz .LBB0_280
	s_barrier
